# 2-phase K-loop without s_setprio flips
# baseline (speedup 1.0000x reference)
; #define PG8_STAGE(bufoff, gbase, voff) do { _Pragma("unroll") for (int _i = 0; _i < 2; ++_i) \
;         __builtin_amdgcn_global_load_lds((const unsigned*)((const char*)(gbase) + (voff)[_i]), (LAS unsigned*)(lds + (bufoff) + ldsw + _i * 8192), 16, 0, 0); } while (0)
; #define PG8_LDA(dst, b, h) do { _Pragma("unroll") for (int m = 0; m < 4; ++m) _Pragma("unroll") for (int k = 0; k < 2; ++k) dst[m][k] = *(const LAS bf16x8*)(lds + PG8_SA(b, h) + aoff + m * 2048 + k * 1024); } while (0)
; #define PG8_LDB(dst, b, h) do { _Pragma("unroll") for (int n = 0; n < 2; ++n) _Pragma("unroll") for (int k = 0; k < 2; ++k) dst[n][k] = *(const LAS bf16x8*)(lds + PG8_SB(b, h) + boff + n * 2048 + k * 1024); } while (0)
; #define PG8_WAIT_V(n) asm volatile("s_waitcnt vmcnt(" #n ")" ::: "memory")
; #define PG8_WAIT_L(n) asm volatile("s_waitcnt lgkmcnt(" #n ")" ::: "memory")
; #define PG8_BAR __builtin_amdgcn_s_barrier()
; #define PG8_SCHED __builtin_amdgcn_sched_barrier(0)
; template <class Epi>
; __device__ __forceinline__ void gemm_phase(LAS unsigned char* lds, const Gemm g, const StaticOrder& S, const Epi& E) {
;     ...
;         const bool has_next = S.next(ui + 1, nxt);
;         const char* nA = has_next ? (const char*)g.A + (size_t)nxt.pm * tstepA : cA; const char* nB = has_next ? (const char*)g.Bt + (size_t)nxt.pn * tstepB : cB;
;         for (int t = 0; t < nt; t += 2) {
;             const bool last = (t == nt - 2);
;             const char* a1 = cA + (size_t)(t + 1) * kstep;
;             const char* a2 = last ? nA : cA + (size_t)(t + 2) * kstep; const char* b2 = last ? nB : cB + (size_t)(t + 2) * kstep;
;             const char* a3 = a2 + kstep; const char* b3 = b2 + kstep;
;             PG8_LDB(B0, 0, 0); PG8_SCHED; PG8_LDA(At, 0, 0); PG8_STAGE(PG8_SA(1, 1), a1 + hstepA, voffA);
;             PG8_WAIT_L(8); PG8_BAR; PG8_WAIT_L(0); PG8_MMA(0, 0, At, B0); PG8_BAR; PG8_SCHED;
;             PG8_LDB(B1, 0, 1); PG8_STAGE(PG8_SB(0, 0), b2, voffB);
;             PG8_BAR; PG8_WAIT_L(0); PG8_MMA(0, 1, At, B1); PG8_BAR;
;             PG8_LDA(At, 0, 1); PG8_STAGE(PG8_SA(0, 0), a2, voffA);
;             PG8_BAR; PG8_WAIT_L(0); PG8_MMA(1, 0, At, B0); PG8_BAR; PG8_SCHED;
;             PG8_STAGE(PG8_SB(0, 1), b2 + hstepB, voffB);
;             PG8_WAIT_V(6); PG8_BAR; PG8_MMA(1, 1, At, B1); PG8_BAR;
.LBB0_140:
	v_mov_b64_e32 v[0:1], 0x800
	s_ashr_i32 s15, s14, 31
	v_cmp_lt_i64_e32 vcc, s[16:17], v[0:1]
	s_lshl_b64 s[16:17], s[14:15], 20
	v_readlane_b32 s18, v252, 53
	v_readlane_b32 s19, v252, 54
	s_add_u32 s16, s18, s16
	s_addc_u32 s17, s19, s17
	s_and_b64 s[18:19], vcc, exec
	s_cselect_b32 s15, s17, s23
	s_cselect_b32 s49, s16, s22
	s_ashr_i32 s5, s4, 31
	s_lshl_b64 s[18:19], s[4:5], 20
	s_add_u32 s18, s34, s18
	s_addc_u32 s19, s35, s19
	s_and_b64 s[26:27], vcc, exec
	s_cselect_b32 s5, s19, s25
	s_cselect_b32 s50, s18, s24
	s_add_u32 s22, s22, 0x84000
	s_addc_u32 s23, s23, 0
	s_add_u32 s51, s24, 0x8000
	s_addc_u32 s52, s25, 0
	s_mov_b32 s54, -2
	s_add_u32 s24, s22, 0xfff84000
	s_addc_u32 s25, s23, -1
	s_cmp_eq_u32 s54, 28
	s_cselect_b32 s28, s49, s24
	s_cselect_b32 s29, s15, s25
	s_cselect_b32 s24, s50, s51
	s_cselect_b32 s25, s5, s52
	s_add_u32 s26, s28, 0x4000
	s_addc_u32 s27, s29, 0
	s_add_i32 m0, s37, 0xc000
	v_lshl_add_u64 v[188:189], s[22:23], 0, v[128:129]
	global_load_lds_dwordx4 v[188:189], off
	s_add_i32 m0, s37, 0xe000
	v_lshl_add_u64 v[188:189], s[22:23], 0, v[130:131]
	global_load_lds_dwordx4 v[188:189], off
	s_mov_b32 s55, 0x10000
	v_add_u32_e32 v148, s55, v134
	ds_read_b128 v[136:139], v148
	ds_read_b128 v[144:147], v148 offset:2048
	ds_read_b128 v[140:143], v148 offset:1024
	ds_read_b128 v[148:151], v148 offset:3072
	ds_read_b128 v[156:159], v135
	ds_read_b128 v[164:167], v135 offset:2048
	ds_read_b128 v[172:175], v135 offset:4096
	ds_read_b128 v[180:183], v135 offset:6144
	ds_read_b128 v[160:163], v135 offset:1024
	ds_read_b128 v[168:171], v135 offset:3072
	ds_read_b128 v[176:179], v135 offset:5120
	ds_read_b128 v[184:187], v135 offset:7168
	s_mov_b32 s58, 0x14000
	s_add_i32 s55, s55, s36
	v_add_u32_e32 v152, s58, v134
	ds_read_b128 v[188:191], v152
	ds_read_b128 v[196:199], v152 offset:2048
	ds_read_b128 v[192:195], v152 offset:1024
	ds_read_b128 v[200:203], v152 offset:3072
	s_waitcnt lgkmcnt(0)
	s_barrier
	v_mfma_f32_16x16x32_bf16 v[124:127], v[136:139], v[156:159], 0
	v_mfma_f32_16x16x32_bf16 v[120:123], v[144:147], v[156:159], 0
	v_mfma_f32_16x16x32_bf16 v[108:111], v[136:139], v[164:167], 0
	v_mfma_f32_16x16x32_bf16 v[104:107], v[144:147], v[164:167], 0
	v_mfma_f32_16x16x32_bf16 v[92:95], v[136:139], v[172:175], 0
	v_mfma_f32_16x16x32_bf16 v[88:91], v[144:147], v[172:175], 0
	v_mfma_f32_16x16x32_bf16 v[76:79], v[136:139], v[180:183], 0
	v_mfma_f32_16x16x32_bf16 v[72:75], v[144:147], v[180:183], 0
	v_mfma_f32_16x16x32_bf16 v[124:127], v[140:143], v[160:163], v[124:127]
	v_mfma_f32_16x16x32_bf16 v[120:123], v[148:151], v[160:163], v[120:123]
	v_mfma_f32_16x16x32_bf16 v[108:111], v[140:143], v[168:171], v[108:111]
	v_mfma_f32_16x16x32_bf16 v[104:107], v[148:151], v[168:171], v[104:107]
	v_mfma_f32_16x16x32_bf16 v[92:95], v[140:143], v[176:179], v[92:95]
	v_mfma_f32_16x16x32_bf16 v[88:91], v[148:151], v[176:179], v[88:91]
	v_mfma_f32_16x16x32_bf16 v[76:79], v[140:143], v[184:187], v[76:79]
	v_mfma_f32_16x16x32_bf16 v[72:75], v[148:151], v[184:187], v[72:75]
	v_mfma_f32_16x16x32_bf16 v[116:119], v[188:191], v[156:159], 0
	v_mfma_f32_16x16x32_bf16 v[112:115], v[196:199], v[156:159], 0
	v_mfma_f32_16x16x32_bf16 v[100:103], v[188:191], v[164:167], 0
	v_mfma_f32_16x16x32_bf16 v[96:99], v[196:199], v[164:167], 0
	v_mfma_f32_16x16x32_bf16 v[84:87], v[188:191], v[172:175], 0
	v_mfma_f32_16x16x32_bf16 v[80:83], v[196:199], v[172:175], 0
	v_mfma_f32_16x16x32_bf16 v[68:71], v[188:191], v[180:183], 0
	v_mfma_f32_16x16x32_bf16 v[64:67], v[196:199], v[180:183], 0
	v_mfma_f32_16x16x32_bf16 v[116:119], v[192:195], v[160:163], v[116:119]
	v_mfma_f32_16x16x32_bf16 v[112:115], v[200:203], v[160:163], v[112:115]
	v_mfma_f32_16x16x32_bf16 v[100:103], v[192:195], v[168:171], v[100:103]
	v_mfma_f32_16x16x32_bf16 v[96:99], v[200:203], v[168:171], v[96:99]
	v_mfma_f32_16x16x32_bf16 v[84:87], v[192:195], v[176:179], v[84:87]
	v_mfma_f32_16x16x32_bf16 v[80:83], v[200:203], v[176:179], v[80:83]
	v_mfma_f32_16x16x32_bf16 v[68:71], v[192:195], v[184:187], v[68:71]
	v_mfma_f32_16x16x32_bf16 v[64:67], v[200:203], v[184:187], v[64:67]
	s_barrier
	s_mov_b32 m0, s55
	v_lshl_add_u64 v[204:205], s[24:25], 0, v[128:129]
	global_load_lds_dwordx4 v[204:205], off
	s_add_i32 m0, s55, 0x2000
	v_lshl_add_u64 v[204:205], s[24:25], 0, v[130:131]
	global_load_lds_dwordx4 v[204:205], off
	s_mov_b32 m0, s37
	v_lshl_add_u64 v[204:205], s[28:29], 0, v[128:129]
	global_load_lds_dwordx4 v[204:205], off
	s_mov_b32 m0, s38
	v_lshl_add_u64 v[204:205], s[28:29], 0, v[130:131]
	global_load_lds_dwordx4 v[204:205], off
	s_add_u32 s56, s24, 0x80000
	s_addc_u32 s57, s25, 0
	s_add_i32 s55, s58, s36
	s_mov_b32 m0, s55
	v_lshl_add_u64 v[204:205], s[56:57], 0, v[128:129]
	global_load_lds_dwordx4 v[204:205], off
	s_add_i32 m0, s55, 0x2000
	v_lshl_add_u64 v[204:205], s[56:57], 0, v[130:131]
	global_load_lds_dwordx4 v[204:205], off
	ds_read_b128 v[156:159], v135 offset:16384
	ds_read_b128 v[164:167], v135 offset:18432
	ds_read_b128 v[172:175], v135 offset:20480
	ds_read_b128 v[180:183], v135 offset:22528
	ds_read_b128 v[160:163], v135 offset:17408
	ds_read_b128 v[168:171], v135 offset:19456
	ds_read_b128 v[176:179], v135 offset:21504
	ds_read_b128 v[184:187], v135 offset:23552
	s_waitcnt vmcnt(6)
	s_waitcnt lgkmcnt(0)
	s_barrier
; #define PG8_STAGE(bufoff, gbase, voff) do { _Pragma("unroll") for (int _i = 0; _i < 2; ++_i) \
;         __builtin_amdgcn_global_load_lds((const unsigned*)((const char*)(gbase) + (voff)[_i]), (LAS unsigned*)(lds + (bufoff) + ldsw + _i * 8192), 16, 0, 0); } while (0)
; #define PG8_LDA(dst, b, h) do { _Pragma("unroll") for (int m = 0; m < 4; ++m) _Pragma("unroll") for (int k = 0; k < 2; ++k) dst[m][k] = *(const LAS bf16x8*)(lds + PG8_SA(b, h) + aoff + m * 2048 + k * 1024); } while (0)
; #define PG8_LDB(dst, b, h) do { _Pragma("unroll") for (int n = 0; n < 2; ++n) _Pragma("unroll") for (int k = 0; k < 2; ++k) dst[n][k] = *(const LAS bf16x8*)(lds + PG8_SB(b, h) + boff + n * 2048 + k * 1024); } while (0)
; #define PG8_MMA(ai, bj, At, Bt) do { __builtin_amdgcn_s_setprio(1); _Pragma("unroll") for (int m = 0; m < 4; ++m) _Pragma("unroll") for (int n = 0; n < 2; ++n) _Pragma("unroll") for (int k = 0; k < 2; ++k) \
;         acc[ai][bj][m][n] = __builtin_amdgcn_mfma_f32_16x16x32_bf16(Bt[n][k], At[m][k], acc[ai][bj][m][n], 0, 0, 0); __builtin_amdgcn_s_setprio(0); } while (0)
; #define PG8_WAIT_V(n) asm volatile("s_waitcnt vmcnt(" #n ")" ::: "memory")
; #define PG8_WAIT_L(n) asm volatile("s_waitcnt lgkmcnt(" #n ")" ::: "memory")
; #define PG8_BAR __builtin_amdgcn_s_barrier()
; #define PG8_SCHED __builtin_amdgcn_sched_barrier(0)
; template <class Epi>
; __device__ __forceinline__ void gemm_phase(LAS unsigned char* lds, const Gemm g, const StaticOrder& S, const Epi& E) {
;     ...
;             PG8_BAR; PG8_WAIT_L(0); PG8_MMA(1, 0, At, B0); PG8_BAR; PG8_SCHED;
;             PG8_STAGE(PG8_SB(0, 1), b2 + hstepB, voffB);
;             PG8_WAIT_V(6); PG8_BAR; PG8_MMA(1, 1, At, B1); PG8_BAR;
;             PG8_LDB(B0, 1, 0); PG8_SCHED; PG8_LDA(At, 1, 0); PG8_STAGE(PG8_SA(0, 1), a2 + hstepA, voffA);
;             PG8_WAIT_L(8); PG8_BAR; PG8_WAIT_L(0); PG8_MMA(0, 0, At, B0); PG8_BAR; PG8_SCHED;
;             PG8_LDB(B1, 1, 1); PG8_STAGE(PG8_SB(1, 0), b3, voffB);
;             PG8_BAR; PG8_WAIT_L(0); PG8_MMA(0, 1, At, B1); PG8_BAR;
;             PG8_LDA(At, 1, 1); PG8_STAGE(PG8_SA(1, 0), a3, voffA);
;             PG8_BAR; PG8_WAIT_L(0); PG8_MMA(1, 0, At, B0); PG8_BAR; PG8_SCHED;
	v_mfma_f32_16x16x32_bf16 v[60:63], v[136:139], v[156:159], 0
	v_mfma_f32_16x16x32_bf16 v[56:59], v[144:147], v[156:159], 0
	v_mfma_f32_16x16x32_bf16 v[44:47], v[136:139], v[164:167], 0
	v_mfma_f32_16x16x32_bf16 v[40:43], v[144:147], v[164:167], 0
	v_mfma_f32_16x16x32_bf16 v[28:31], v[136:139], v[172:175], 0
	v_mfma_f32_16x16x32_bf16 v[24:27], v[144:147], v[172:175], 0
	v_mfma_f32_16x16x32_bf16 v[12:15], v[136:139], v[180:183], 0
	v_mfma_f32_16x16x32_bf16 v[8:11], v[144:147], v[180:183], 0
	v_mfma_f32_16x16x32_bf16 v[60:63], v[140:143], v[160:163], v[60:63]
	v_mfma_f32_16x16x32_bf16 v[56:59], v[148:151], v[160:163], v[56:59]
	v_mfma_f32_16x16x32_bf16 v[44:47], v[140:143], v[168:171], v[44:47]
	v_mfma_f32_16x16x32_bf16 v[40:43], v[148:151], v[168:171], v[40:43]
	v_mfma_f32_16x16x32_bf16 v[28:31], v[140:143], v[176:179], v[28:31]
	v_mfma_f32_16x16x32_bf16 v[24:27], v[148:151], v[176:179], v[24:27]
	v_mfma_f32_16x16x32_bf16 v[12:15], v[140:143], v[184:187], v[12:15]
	v_mfma_f32_16x16x32_bf16 v[8:11], v[148:151], v[184:187], v[8:11]
	v_mfma_f32_16x16x32_bf16 v[52:55], v[188:191], v[156:159], 0
	v_mfma_f32_16x16x32_bf16 v[48:51], v[196:199], v[156:159], 0
	s_add_i32 s55, 0, 0x18000
	v_add_u32_e32 v148, s55, v134
	v_mfma_f32_16x16x32_bf16 v[36:39], v[188:191], v[164:167], 0
	v_mfma_f32_16x16x32_bf16 v[32:35], v[196:199], v[164:167], 0
	v_mfma_f32_16x16x32_bf16 v[20:23], v[188:191], v[172:175], 0
	v_mfma_f32_16x16x32_bf16 v[16:19], v[196:199], v[172:175], 0
	v_mfma_f32_16x16x32_bf16 v[4:7], v[188:191], v[180:183], 0
	v_mfma_f32_16x16x32_bf16 v[0:3], v[196:199], v[180:183], 0
	v_mfma_f32_16x16x32_bf16 v[52:55], v[192:195], v[160:163], v[52:55]
	v_mfma_f32_16x16x32_bf16 v[48:51], v[200:203], v[160:163], v[48:51]
	v_mfma_f32_16x16x32_bf16 v[36:39], v[192:195], v[168:171], v[36:39]
	v_mfma_f32_16x16x32_bf16 v[32:35], v[200:203], v[168:171], v[32:35]
	v_mfma_f32_16x16x32_bf16 v[20:23], v[192:195], v[176:179], v[20:23]
	v_mfma_f32_16x16x32_bf16 v[16:19], v[200:203], v[176:179], v[16:19]
	v_mfma_f32_16x16x32_bf16 v[4:7], v[192:195], v[184:187], v[4:7]
	v_mfma_f32_16x16x32_bf16 v[0:3], v[200:203], v[184:187], v[0:3]
	s_barrier
	s_add_u32 s28, s28, 0x80000
	s_addc_u32 s29, s29, 0
	s_mov_b32 m0, s39
	v_lshl_add_u64 v[188:189], s[28:29], 0, v[128:129]
	global_load_lds_dwordx4 v[188:189], off
	s_mov_b32 m0, s40
	v_lshl_add_u64 v[188:189], s[28:29], 0, v[130:131]
	global_load_lds_dwordx4 v[188:189], off
	ds_read_b128 v[136:139], v148
	ds_read_b128 v[144:147], v148 offset:2048
	ds_read_b128 v[140:143], v148 offset:1024
	ds_read_b128 v[148:151], v148 offset:3072
	ds_read_b128 v[156:159], v135 offset:32768
	ds_read_b128 v[164:167], v135 offset:34816
	ds_read_b128 v[172:175], v135 offset:36864
	ds_read_b128 v[180:183], v135 offset:38912
	ds_read_b128 v[160:163], v135 offset:33792
	ds_read_b128 v[168:171], v135 offset:35840
	ds_read_b128 v[176:179], v135 offset:37888
	ds_read_b128 v[184:187], v135 offset:39936
	s_mov_b32 s56, 0x1c000
	s_add_u32 s28, s24, 0x4000
	s_addc_u32 s29, s25, 0
	s_add_i32 s55, s55, s36
	v_add_u32_e32 v152, s56, v134
	ds_read_b128 v[188:191], v152
	ds_read_b128 v[196:199], v152 offset:2048
	ds_read_b128 v[192:195], v152 offset:1024
	ds_read_b128 v[200:203], v152 offset:3072
	s_waitcnt lgkmcnt(0)
	s_barrier
	v_mfma_f32_16x16x32_bf16 v[124:127], v[136:139], v[156:159], v[124:127]
	v_mfma_f32_16x16x32_bf16 v[120:123], v[144:147], v[156:159], v[120:123]
	v_mfma_f32_16x16x32_bf16 v[108:111], v[136:139], v[164:167], v[108:111]
	v_mfma_f32_16x16x32_bf16 v[104:107], v[144:147], v[164:167], v[104:107]
	v_mfma_f32_16x16x32_bf16 v[92:95], v[136:139], v[172:175], v[92:95]
	v_mfma_f32_16x16x32_bf16 v[88:91], v[144:147], v[172:175], v[88:91]
	v_mfma_f32_16x16x32_bf16 v[76:79], v[136:139], v[180:183], v[76:79]
	v_mfma_f32_16x16x32_bf16 v[72:75], v[144:147], v[180:183], v[72:75]
	v_mfma_f32_16x16x32_bf16 v[124:127], v[140:143], v[160:163], v[124:127]
	v_mfma_f32_16x16x32_bf16 v[120:123], v[148:151], v[160:163], v[120:123]
	v_mfma_f32_16x16x32_bf16 v[108:111], v[140:143], v[168:171], v[108:111]
	v_mfma_f32_16x16x32_bf16 v[104:107], v[148:151], v[168:171], v[104:107]
	v_mfma_f32_16x16x32_bf16 v[92:95], v[140:143], v[176:179], v[92:95]
	v_mfma_f32_16x16x32_bf16 v[88:91], v[148:151], v[176:179], v[88:91]
	v_mfma_f32_16x16x32_bf16 v[76:79], v[140:143], v[184:187], v[76:79]
	v_mfma_f32_16x16x32_bf16 v[72:75], v[148:151], v[184:187], v[72:75]
	v_mfma_f32_16x16x32_bf16 v[116:119], v[188:191], v[156:159], v[116:119]
	v_mfma_f32_16x16x32_bf16 v[112:115], v[196:199], v[156:159], v[112:115]
	v_mfma_f32_16x16x32_bf16 v[100:103], v[188:191], v[164:167], v[100:103]
	v_mfma_f32_16x16x32_bf16 v[96:99], v[196:199], v[164:167], v[96:99]
	v_mfma_f32_16x16x32_bf16 v[84:87], v[188:191], v[172:175], v[84:87]
	v_mfma_f32_16x16x32_bf16 v[80:83], v[196:199], v[172:175], v[80:83]
	v_mfma_f32_16x16x32_bf16 v[68:71], v[188:191], v[180:183], v[68:71]
	v_mfma_f32_16x16x32_bf16 v[64:67], v[196:199], v[180:183], v[64:67]
	v_mfma_f32_16x16x32_bf16 v[116:119], v[192:195], v[160:163], v[116:119]
	v_mfma_f32_16x16x32_bf16 v[112:115], v[200:203], v[160:163], v[112:115]
	v_mfma_f32_16x16x32_bf16 v[100:103], v[192:195], v[168:171], v[100:103]
	v_mfma_f32_16x16x32_bf16 v[96:99], v[200:203], v[168:171], v[96:99]
	v_mfma_f32_16x16x32_bf16 v[84:87], v[192:195], v[176:179], v[84:87]
	v_mfma_f32_16x16x32_bf16 v[80:83], v[200:203], v[176:179], v[80:83]
	v_mfma_f32_16x16x32_bf16 v[68:71], v[192:195], v[184:187], v[68:71]
	v_mfma_f32_16x16x32_bf16 v[64:67], v[200:203], v[184:187], v[64:67]
	s_barrier
; #define PG8_STAGE(bufoff, gbase, voff) do { _Pragma("unroll") for (int _i = 0; _i < 2; ++_i) \
;         __builtin_amdgcn_global_load_lds((const unsigned*)((const char*)(gbase) + (voff)[_i]), (LAS unsigned*)(lds + (bufoff) + ldsw + _i * 8192), 16, 0, 0); } while (0)
; #define PG8_LDA(dst, b, h) do { _Pragma("unroll") for (int m = 0; m < 4; ++m) _Pragma("unroll") for (int k = 0; k < 2; ++k) dst[m][k] = *(const LAS bf16x8*)(lds + PG8_SA(b, h) + aoff + m * 2048 + k * 1024); } while (0)
; #define PG8_LDB(dst, b, h) do { _Pragma("unroll") for (int n = 0; n < 2; ++n) _Pragma("unroll") for (int k = 0; k < 2; ++k) dst[n][k] = *(const LAS bf16x8*)(lds + PG8_SB(b, h) + boff + n * 2048 + k * 1024); } while (0)
; #define PG8_MMA(ai, bj, At, Bt) do { __builtin_amdgcn_s_setprio(1); _Pragma("unroll") for (int m = 0; m < 4; ++m) _Pragma("unroll") for (int n = 0; n < 2; ++n) _Pragma("unroll") for (int k = 0; k < 2; ++k) \
;         acc[ai][bj][m][n] = __builtin_amdgcn_mfma_f32_16x16x32_bf16(Bt[n][k], At[m][k], acc[ai][bj][m][n], 0, 0, 0); __builtin_amdgcn_s_setprio(0); } while (0)
; #define PG8_WAIT_V(n) asm volatile("s_waitcnt vmcnt(" #n ")" ::: "memory")
; #define PG8_WAIT_L(n) asm volatile("s_waitcnt lgkmcnt(" #n ")" ::: "memory")
; #define PG8_BAR __builtin_amdgcn_s_barrier()
; #define PG8_SCHED __builtin_amdgcn_sched_barrier(0)
; template <class Epi>
; __device__ __forceinline__ void gemm_phase(LAS unsigned char* lds, const Gemm g, const StaticOrder& S, const Epi& E) {
;     ...
;         for (int t = 0; t < nt; t += 2) {
;             const bool last = (t == nt - 2);
;             const char* a1 = cA + (size_t)(t + 1) * kstep;
;             const char* a2 = last ? nA : cA + (size_t)(t + 2) * kstep; const char* b2 = last ? nB : cB + (size_t)(t + 2) * kstep;
;             const char* a3 = a2 + kstep; const char* b3 = b2 + kstep;
;             PG8_LDB(B0, 0, 0); PG8_SCHED; PG8_LDA(At, 0, 0); PG8_STAGE(PG8_SA(1, 1), a1 + hstepA, voffA);
;             PG8_WAIT_L(8); PG8_BAR; PG8_WAIT_L(0); PG8_MMA(0, 0, At, B0); PG8_BAR; PG8_SCHED;
;     ...
;             PG8_BAR; PG8_WAIT_L(0); PG8_MMA(0, 1, At, B1); PG8_BAR;
;             PG8_LDA(At, 1, 1); PG8_STAGE(PG8_SA(1, 0), a3, voffA);
;             PG8_BAR; PG8_WAIT_L(0); PG8_MMA(1, 0, At, B0); PG8_BAR; PG8_SCHED;
;             PG8_STAGE(PG8_SB(1, 1), b3 + hstepB, voffB);
;             PG8_WAIT_V(6); PG8_BAR; PG8_MMA(1, 1, At, B1); PG8_BAR;
	s_mov_b32 m0, s55
	v_lshl_add_u64 v[204:205], s[28:29], 0, v[128:129]
	global_load_lds_dwordx4 v[204:205], off
	s_add_i32 m0, s55, 0x2000
	v_lshl_add_u64 v[204:205], s[28:29], 0, v[130:131]
	global_load_lds_dwordx4 v[204:205], off
	s_mov_b32 m0, s43
	v_lshl_add_u64 v[204:205], s[26:27], 0, v[128:129]
	global_load_lds_dwordx4 v[204:205], off
	s_mov_b32 m0, s44
	v_lshl_add_u64 v[204:205], s[26:27], 0, v[130:131]
	global_load_lds_dwordx4 v[204:205], off
	s_add_u32 s24, s24, 0x84000
	s_addc_u32 s25, s25, 0
	s_add_i32 s26, s56, s36
	s_mov_b32 m0, s26
	v_lshl_add_u64 v[204:205], s[24:25], 0, v[128:129]
	global_load_lds_dwordx4 v[204:205], off
	s_add_i32 m0, s26, 0x2000
	v_lshl_add_u64 v[204:205], s[24:25], 0, v[130:131]
	global_load_lds_dwordx4 v[204:205], off
	ds_read_b128 v[156:159], v135 offset:49152
	ds_read_b128 v[164:167], v135 offset:51200
	ds_read_b128 v[172:175], v135 offset:53248
	ds_read_b128 v[180:183], v135 offset:55296
	ds_read_b128 v[160:163], v135 offset:50176
	ds_read_b128 v[168:171], v135 offset:52224
	ds_read_b128 v[176:179], v135 offset:54272
	ds_read_b128 v[184:187], v135 offset:56320
	s_waitcnt vmcnt(6)
	s_waitcnt lgkmcnt(0)
	s_barrier
	v_mfma_f32_16x16x32_bf16 v[60:63], v[136:139], v[156:159], v[60:63]
	v_mfma_f32_16x16x32_bf16 v[56:59], v[144:147], v[156:159], v[56:59]
	v_mfma_f32_16x16x32_bf16 v[44:47], v[136:139], v[164:167], v[44:47]
	v_mfma_f32_16x16x32_bf16 v[40:43], v[144:147], v[164:167], v[40:43]
	v_mfma_f32_16x16x32_bf16 v[28:31], v[136:139], v[172:175], v[28:31]
	v_mfma_f32_16x16x32_bf16 v[24:27], v[144:147], v[172:175], v[24:27]
	v_mfma_f32_16x16x32_bf16 v[12:15], v[136:139], v[180:183], v[12:15]
	v_mfma_f32_16x16x32_bf16 v[8:11], v[144:147], v[180:183], v[8:11]
	v_mfma_f32_16x16x32_bf16 v[60:63], v[140:143], v[160:163], v[60:63]
	v_mfma_f32_16x16x32_bf16 v[56:59], v[148:151], v[160:163], v[56:59]
	v_mfma_f32_16x16x32_bf16 v[44:47], v[140:143], v[168:171], v[44:47]
	v_mfma_f32_16x16x32_bf16 v[40:43], v[148:151], v[168:171], v[40:43]
	v_mfma_f32_16x16x32_bf16 v[28:31], v[140:143], v[176:179], v[28:31]
	v_mfma_f32_16x16x32_bf16 v[24:27], v[148:151], v[176:179], v[24:27]
	v_mfma_f32_16x16x32_bf16 v[12:15], v[140:143], v[184:187], v[12:15]
	v_mfma_f32_16x16x32_bf16 v[8:11], v[148:151], v[184:187], v[8:11]
	v_mfma_f32_16x16x32_bf16 v[52:55], v[188:191], v[156:159], v[52:55]
	v_mfma_f32_16x16x32_bf16 v[48:51], v[196:199], v[156:159], v[48:51]
	s_add_i32 s54, s54, 2
	s_add_u32 s22, s22, 0x8000
	s_addc_u32 s23, s23, 0
	s_add_u32 s51, s51, 0x8000
	s_addc_u32 s52, s52, 0
	v_mfma_f32_16x16x32_bf16 v[36:39], v[188:191], v[164:167], v[36:39]
	v_mfma_f32_16x16x32_bf16 v[32:35], v[196:199], v[164:167], v[32:35]
	v_mfma_f32_16x16x32_bf16 v[20:23], v[188:191], v[172:175], v[20:23]
	v_mfma_f32_16x16x32_bf16 v[16:19], v[196:199], v[172:175], v[16:19]
	v_mfma_f32_16x16x32_bf16 v[4:7], v[188:191], v[180:183], v[4:7]
	v_mfma_f32_16x16x32_bf16 v[0:3], v[196:199], v[180:183], v[0:3]
	v_mfma_f32_16x16x32_bf16 v[52:55], v[192:195], v[160:163], v[52:55]
	v_mfma_f32_16x16x32_bf16 v[48:51], v[200:203], v[160:163], v[48:51]
	v_mfma_f32_16x16x32_bf16 v[36:39], v[192:195], v[168:171], v[36:39]
	v_mfma_f32_16x16x32_bf16 v[32:35], v[200:203], v[168:171], v[32:35]
	v_mfma_f32_16x16x32_bf16 v[20:23], v[192:195], v[176:179], v[20:23]
	v_mfma_f32_16x16x32_bf16 v[16:19], v[200:203], v[176:179], v[16:19]
	v_mfma_f32_16x16x32_bf16 v[4:7], v[192:195], v[184:187], v[4:7]
	s_cmp_gt_u32 s54, 29
	v_mfma_f32_16x16x32_bf16 v[0:3], v[200:203], v[184:187], v[0:3]
	s_barrier
	s_cbranch_scc0 .LBB0_141
	s_branch .Lpeel_done_141
.LBB0_141:
	s_add_u32 s24, s22, 0xfff84000
	s_addc_u32 s25, s23, -1
	s_cmp_eq_u32 s54, 28
	s_cselect_b32 s28, s49, s24
	s_cselect_b32 s29, s15, s25
	s_cselect_b32 s24, s50, s51
	s_cselect_b32 s25, s5, s52
	s_add_u32 s26, s28, 0x4000
	s_addc_u32 s27, s29, 0
	s_add_i32 m0, s37, 0xc000
	v_lshl_add_u64 v[188:189], s[22:23], 0, v[128:129]
	global_load_lds_dwordx4 v[188:189], off
	s_add_i32 m0, s37, 0xe000
	v_lshl_add_u64 v[188:189], s[22:23], 0, v[130:131]
	global_load_lds_dwordx4 v[188:189], off
	s_mov_b32 s55, 0x10000
	v_add_u32_e32 v148, s55, v134
	ds_read_b128 v[136:139], v148
	ds_read_b128 v[144:147], v148 offset:2048
	ds_read_b128 v[140:143], v148 offset:1024
	ds_read_b128 v[148:151], v148 offset:3072
	ds_read_b128 v[156:159], v135
	ds_read_b128 v[164:167], v135 offset:2048
	ds_read_b128 v[172:175], v135 offset:4096
	ds_read_b128 v[180:183], v135 offset:6144
	ds_read_b128 v[160:163], v135 offset:1024
	ds_read_b128 v[168:171], v135 offset:3072
	ds_read_b128 v[176:179], v135 offset:5120
	ds_read_b128 v[184:187], v135 offset:7168
	s_mov_b32 s58, 0x14000
	s_add_i32 s55, s55, s36
	v_add_u32_e32 v152, s58, v134
	ds_read_b128 v[188:191], v152
	ds_read_b128 v[196:199], v152 offset:2048
	ds_read_b128 v[192:195], v152 offset:1024
	ds_read_b128 v[200:203], v152 offset:3072
	s_waitcnt lgkmcnt(0)
	s_barrier
; #define PG8_STAGE(bufoff, gbase, voff) do { _Pragma("unroll") for (int _i = 0; _i < 2; ++_i) \
;         __builtin_amdgcn_global_load_lds((const unsigned*)((const char*)(gbase) + (voff)[_i]), (LAS unsigned*)(lds + (bufoff) + ldsw + _i * 8192), 16, 0, 0); } while (0)
; #define PG8_LDA(dst, b, h) do { _Pragma("unroll") for (int m = 0; m < 4; ++m) _Pragma("unroll") for (int k = 0; k < 2; ++k) dst[m][k] = *(const LAS bf16x8*)(lds + PG8_SA(b, h) + aoff + m * 2048 + k * 1024); } while (0)
; #define PG8_LDB(dst, b, h) do { _Pragma("unroll") for (int n = 0; n < 2; ++n) _Pragma("unroll") for (int k = 0; k < 2; ++k) dst[n][k] = *(const LAS bf16x8*)(lds + PG8_SB(b, h) + boff + n * 2048 + k * 1024); } while (0)
; #define PG8_MMA(ai, bj, At, Bt) do { __builtin_amdgcn_s_setprio(1); _Pragma("unroll") for (int m = 0; m < 4; ++m) _Pragma("unroll") for (int n = 0; n < 2; ++n) _Pragma("unroll") for (int k = 0; k < 2; ++k) \
;         acc[ai][bj][m][n] = __builtin_amdgcn_mfma_f32_16x16x32_bf16(Bt[n][k], At[m][k], acc[ai][bj][m][n], 0, 0, 0); __builtin_amdgcn_s_setprio(0); } while (0)
; #define PG8_WAIT_V(n) asm volatile("s_waitcnt vmcnt(" #n ")" ::: "memory")
; #define PG8_WAIT_L(n) asm volatile("s_waitcnt lgkmcnt(" #n ")" ::: "memory")
; #define PG8_BAR __builtin_amdgcn_s_barrier()
; #define PG8_SCHED __builtin_amdgcn_sched_barrier(0)
; template <class Epi>
; __device__ __forceinline__ void gemm_phase(LAS unsigned char* lds, const Gemm g, const StaticOrder& S, const Epi& E) {
;     ...
;             PG8_WAIT_L(8); PG8_BAR; PG8_WAIT_L(0); PG8_MMA(0, 0, At, B0); PG8_BAR; PG8_SCHED;
;             PG8_LDB(B1, 0, 1); PG8_STAGE(PG8_SB(0, 0), b2, voffB);
;             PG8_BAR; PG8_WAIT_L(0); PG8_MMA(0, 1, At, B1); PG8_BAR;
;             PG8_LDA(At, 0, 1); PG8_STAGE(PG8_SA(0, 0), a2, voffA);
;             PG8_BAR; PG8_WAIT_L(0); PG8_MMA(1, 0, At, B0); PG8_BAR; PG8_SCHED;
;             PG8_STAGE(PG8_SB(0, 1), b2 + hstepB, voffB);
;             PG8_WAIT_V(6); PG8_BAR; PG8_MMA(1, 1, At, B1); PG8_BAR;
;             PG8_LDB(B0, 1, 0); PG8_SCHED; PG8_LDA(At, 1, 0); PG8_STAGE(PG8_SA(0, 1), a2 + hstepA, voffA);
;             PG8_WAIT_L(8); PG8_BAR; PG8_WAIT_L(0); PG8_MMA(0, 0, At, B0); PG8_BAR; PG8_SCHED;
	v_mfma_f32_16x16x32_bf16 v[124:127], v[136:139], v[156:159], v[124:127]
	v_mfma_f32_16x16x32_bf16 v[120:123], v[144:147], v[156:159], v[120:123]
	v_mfma_f32_16x16x32_bf16 v[108:111], v[136:139], v[164:167], v[108:111]
	v_mfma_f32_16x16x32_bf16 v[104:107], v[144:147], v[164:167], v[104:107]
	v_mfma_f32_16x16x32_bf16 v[92:95], v[136:139], v[172:175], v[92:95]
	v_mfma_f32_16x16x32_bf16 v[88:91], v[144:147], v[172:175], v[88:91]
	v_mfma_f32_16x16x32_bf16 v[76:79], v[136:139], v[180:183], v[76:79]
	v_mfma_f32_16x16x32_bf16 v[72:75], v[144:147], v[180:183], v[72:75]
	v_mfma_f32_16x16x32_bf16 v[124:127], v[140:143], v[160:163], v[124:127]
	v_mfma_f32_16x16x32_bf16 v[120:123], v[148:151], v[160:163], v[120:123]
	v_mfma_f32_16x16x32_bf16 v[108:111], v[140:143], v[168:171], v[108:111]
	v_mfma_f32_16x16x32_bf16 v[104:107], v[148:151], v[168:171], v[104:107]
	v_mfma_f32_16x16x32_bf16 v[92:95], v[140:143], v[176:179], v[92:95]
	v_mfma_f32_16x16x32_bf16 v[88:91], v[148:151], v[176:179], v[88:91]
	v_mfma_f32_16x16x32_bf16 v[76:79], v[140:143], v[184:187], v[76:79]
	v_mfma_f32_16x16x32_bf16 v[72:75], v[148:151], v[184:187], v[72:75]
	v_mfma_f32_16x16x32_bf16 v[116:119], v[188:191], v[156:159], v[116:119]
	v_mfma_f32_16x16x32_bf16 v[112:115], v[196:199], v[156:159], v[112:115]
	v_mfma_f32_16x16x32_bf16 v[100:103], v[188:191], v[164:167], v[100:103]
	v_mfma_f32_16x16x32_bf16 v[96:99], v[196:199], v[164:167], v[96:99]
	v_mfma_f32_16x16x32_bf16 v[84:87], v[188:191], v[172:175], v[84:87]
	v_mfma_f32_16x16x32_bf16 v[80:83], v[196:199], v[172:175], v[80:83]
	v_mfma_f32_16x16x32_bf16 v[68:71], v[188:191], v[180:183], v[68:71]
	v_mfma_f32_16x16x32_bf16 v[64:67], v[196:199], v[180:183], v[64:67]
	v_mfma_f32_16x16x32_bf16 v[116:119], v[192:195], v[160:163], v[116:119]
	v_mfma_f32_16x16x32_bf16 v[112:115], v[200:203], v[160:163], v[112:115]
	v_mfma_f32_16x16x32_bf16 v[100:103], v[192:195], v[168:171], v[100:103]
	v_mfma_f32_16x16x32_bf16 v[96:99], v[200:203], v[168:171], v[96:99]
	v_mfma_f32_16x16x32_bf16 v[84:87], v[192:195], v[176:179], v[84:87]
	v_mfma_f32_16x16x32_bf16 v[80:83], v[200:203], v[176:179], v[80:83]
	v_mfma_f32_16x16x32_bf16 v[68:71], v[192:195], v[184:187], v[68:71]
	v_mfma_f32_16x16x32_bf16 v[64:67], v[200:203], v[184:187], v[64:67]
	s_barrier
	s_mov_b32 m0, s55
	v_lshl_add_u64 v[204:205], s[24:25], 0, v[128:129]
	global_load_lds_dwordx4 v[204:205], off
	s_add_i32 m0, s55, 0x2000
	v_lshl_add_u64 v[204:205], s[24:25], 0, v[130:131]
	global_load_lds_dwordx4 v[204:205], off
	s_mov_b32 m0, s37
	v_lshl_add_u64 v[204:205], s[28:29], 0, v[128:129]
	global_load_lds_dwordx4 v[204:205], off
	s_mov_b32 m0, s38
	v_lshl_add_u64 v[204:205], s[28:29], 0, v[130:131]
	global_load_lds_dwordx4 v[204:205], off
	s_add_u32 s56, s24, 0x80000
	s_addc_u32 s57, s25, 0
	s_add_i32 s55, s58, s36
	s_mov_b32 m0, s55
	v_lshl_add_u64 v[204:205], s[56:57], 0, v[128:129]
	global_load_lds_dwordx4 v[204:205], off
	s_add_i32 m0, s55, 0x2000
	v_lshl_add_u64 v[204:205], s[56:57], 0, v[130:131]
	global_load_lds_dwordx4 v[204:205], off
	ds_read_b128 v[156:159], v135 offset:16384
	ds_read_b128 v[164:167], v135 offset:18432
	ds_read_b128 v[172:175], v135 offset:20480
	ds_read_b128 v[180:183], v135 offset:22528
	ds_read_b128 v[160:163], v135 offset:17408
	ds_read_b128 v[168:171], v135 offset:19456
	ds_read_b128 v[176:179], v135 offset:21504
	ds_read_b128 v[184:187], v135 offset:23552
	s_waitcnt vmcnt(6)
	s_waitcnt lgkmcnt(0)
	s_barrier
	v_mfma_f32_16x16x32_bf16 v[60:63], v[136:139], v[156:159], v[60:63]
	v_mfma_f32_16x16x32_bf16 v[56:59], v[144:147], v[156:159], v[56:59]
	v_mfma_f32_16x16x32_bf16 v[44:47], v[136:139], v[164:167], v[44:47]
	v_mfma_f32_16x16x32_bf16 v[40:43], v[144:147], v[164:167], v[40:43]
	v_mfma_f32_16x16x32_bf16 v[28:31], v[136:139], v[172:175], v[28:31]
	v_mfma_f32_16x16x32_bf16 v[24:27], v[144:147], v[172:175], v[24:27]
	v_mfma_f32_16x16x32_bf16 v[12:15], v[136:139], v[180:183], v[12:15]
	v_mfma_f32_16x16x32_bf16 v[8:11], v[144:147], v[180:183], v[8:11]
	v_mfma_f32_16x16x32_bf16 v[60:63], v[140:143], v[160:163], v[60:63]
	v_mfma_f32_16x16x32_bf16 v[56:59], v[148:151], v[160:163], v[56:59]
	v_mfma_f32_16x16x32_bf16 v[44:47], v[140:143], v[168:171], v[44:47]
	v_mfma_f32_16x16x32_bf16 v[40:43], v[148:151], v[168:171], v[40:43]
	v_mfma_f32_16x16x32_bf16 v[28:31], v[140:143], v[176:179], v[28:31]
	v_mfma_f32_16x16x32_bf16 v[24:27], v[148:151], v[176:179], v[24:27]
	v_mfma_f32_16x16x32_bf16 v[12:15], v[140:143], v[184:187], v[12:15]
	v_mfma_f32_16x16x32_bf16 v[8:11], v[148:151], v[184:187], v[8:11]
	v_mfma_f32_16x16x32_bf16 v[52:55], v[188:191], v[156:159], v[52:55]
	v_mfma_f32_16x16x32_bf16 v[48:51], v[196:199], v[156:159], v[48:51]
	s_add_i32 s55, 0, 0x18000
	v_add_u32_e32 v148, s55, v134
	v_mfma_f32_16x16x32_bf16 v[36:39], v[188:191], v[164:167], v[36:39]
	v_mfma_f32_16x16x32_bf16 v[32:35], v[196:199], v[164:167], v[32:35]
	v_mfma_f32_16x16x32_bf16 v[20:23], v[188:191], v[172:175], v[20:23]
	v_mfma_f32_16x16x32_bf16 v[16:19], v[196:199], v[172:175], v[16:19]
	v_mfma_f32_16x16x32_bf16 v[4:7], v[188:191], v[180:183], v[4:7]
	v_mfma_f32_16x16x32_bf16 v[0:3], v[196:199], v[180:183], v[0:3]
	v_mfma_f32_16x16x32_bf16 v[52:55], v[192:195], v[160:163], v[52:55]
	v_mfma_f32_16x16x32_bf16 v[48:51], v[200:203], v[160:163], v[48:51]
	v_mfma_f32_16x16x32_bf16 v[36:39], v[192:195], v[168:171], v[36:39]
	v_mfma_f32_16x16x32_bf16 v[32:35], v[200:203], v[168:171], v[32:35]
	v_mfma_f32_16x16x32_bf16 v[20:23], v[192:195], v[176:179], v[20:23]
	v_mfma_f32_16x16x32_bf16 v[16:19], v[200:203], v[176:179], v[16:19]
	v_mfma_f32_16x16x32_bf16 v[4:7], v[192:195], v[184:187], v[4:7]
	v_mfma_f32_16x16x32_bf16 v[0:3], v[200:203], v[184:187], v[0:3]
	s_barrier
; #define PG8_STAGE(bufoff, gbase, voff) do { _Pragma("unroll") for (int _i = 0; _i < 2; ++_i) \
;         __builtin_amdgcn_global_load_lds((const unsigned*)((const char*)(gbase) + (voff)[_i]), (LAS unsigned*)(lds + (bufoff) + ldsw + _i * 8192), 16, 0, 0); } while (0)
; #define PG8_LDA(dst, b, h) do { _Pragma("unroll") for (int m = 0; m < 4; ++m) _Pragma("unroll") for (int k = 0; k < 2; ++k) dst[m][k] = *(const LAS bf16x8*)(lds + PG8_SA(b, h) + aoff + m * 2048 + k * 1024); } while (0)
; #define PG8_LDB(dst, b, h) do { _Pragma("unroll") for (int n = 0; n < 2; ++n) _Pragma("unroll") for (int k = 0; k < 2; ++k) dst[n][k] = *(const LAS bf16x8*)(lds + PG8_SB(b, h) + boff + n * 2048 + k * 1024); } while (0)
; #define PG8_MMA(ai, bj, At, Bt) do { __builtin_amdgcn_s_setprio(1); _Pragma("unroll") for (int m = 0; m < 4; ++m) _Pragma("unroll") for (int n = 0; n < 2; ++n) _Pragma("unroll") for (int k = 0; k < 2; ++k) \
;         acc[ai][bj][m][n] = __builtin_amdgcn_mfma_f32_16x16x32_bf16(Bt[n][k], At[m][k], acc[ai][bj][m][n], 0, 0, 0); __builtin_amdgcn_s_setprio(0); } while (0)
; #define PG8_WAIT_V(n) asm volatile("s_waitcnt vmcnt(" #n ")" ::: "memory")
; #define PG8_WAIT_L(n) asm volatile("s_waitcnt lgkmcnt(" #n ")" ::: "memory")
; #define PG8_BAR __builtin_amdgcn_s_barrier()
; #define PG8_SCHED __builtin_amdgcn_sched_barrier(0)
; template <class Epi>
; __device__ __forceinline__ void gemm_phase(LAS unsigned char* lds, const Gemm g, const StaticOrder& S, const Epi& E) {
;     ...
;             PG8_LDB(B1, 1, 1); PG8_STAGE(PG8_SB(1, 0), b3, voffB);
;             PG8_BAR; PG8_WAIT_L(0); PG8_MMA(0, 1, At, B1); PG8_BAR;
;             PG8_LDA(At, 1, 1); PG8_STAGE(PG8_SA(1, 0), a3, voffA);
;             PG8_BAR; PG8_WAIT_L(0); PG8_MMA(1, 0, At, B0); PG8_BAR; PG8_SCHED;
;             PG8_STAGE(PG8_SB(1, 1), b3 + hstepB, voffB);
;             PG8_WAIT_V(6); PG8_BAR; PG8_MMA(1, 1, At, B1); PG8_BAR;
	s_add_u32 s28, s28, 0x80000
	s_addc_u32 s29, s29, 0
	s_mov_b32 m0, s39
	v_lshl_add_u64 v[188:189], s[28:29], 0, v[128:129]
	global_load_lds_dwordx4 v[188:189], off
	s_mov_b32 m0, s40
	v_lshl_add_u64 v[188:189], s[28:29], 0, v[130:131]
	global_load_lds_dwordx4 v[188:189], off
	ds_read_b128 v[136:139], v148
	ds_read_b128 v[144:147], v148 offset:2048
	ds_read_b128 v[140:143], v148 offset:1024
	ds_read_b128 v[148:151], v148 offset:3072
	ds_read_b128 v[156:159], v135 offset:32768
	ds_read_b128 v[164:167], v135 offset:34816
	ds_read_b128 v[172:175], v135 offset:36864
	ds_read_b128 v[180:183], v135 offset:38912
	ds_read_b128 v[160:163], v135 offset:33792
	ds_read_b128 v[168:171], v135 offset:35840
	ds_read_b128 v[176:179], v135 offset:37888
	ds_read_b128 v[184:187], v135 offset:39936
	s_mov_b32 s56, 0x1c000
	s_add_u32 s28, s24, 0x4000
	s_addc_u32 s29, s25, 0
	s_add_i32 s55, s55, s36
	v_add_u32_e32 v152, s56, v134
	ds_read_b128 v[188:191], v152
	ds_read_b128 v[196:199], v152 offset:2048
	ds_read_b128 v[192:195], v152 offset:1024
	ds_read_b128 v[200:203], v152 offset:3072
	s_waitcnt lgkmcnt(0)
	s_barrier
	v_mfma_f32_16x16x32_bf16 v[124:127], v[136:139], v[156:159], v[124:127]
	v_mfma_f32_16x16x32_bf16 v[120:123], v[144:147], v[156:159], v[120:123]
	v_mfma_f32_16x16x32_bf16 v[108:111], v[136:139], v[164:167], v[108:111]
	v_mfma_f32_16x16x32_bf16 v[104:107], v[144:147], v[164:167], v[104:107]
	v_mfma_f32_16x16x32_bf16 v[92:95], v[136:139], v[172:175], v[92:95]
	v_mfma_f32_16x16x32_bf16 v[88:91], v[144:147], v[172:175], v[88:91]
	v_mfma_f32_16x16x32_bf16 v[76:79], v[136:139], v[180:183], v[76:79]
	v_mfma_f32_16x16x32_bf16 v[72:75], v[144:147], v[180:183], v[72:75]
	v_mfma_f32_16x16x32_bf16 v[124:127], v[140:143], v[160:163], v[124:127]
	v_mfma_f32_16x16x32_bf16 v[120:123], v[148:151], v[160:163], v[120:123]
	v_mfma_f32_16x16x32_bf16 v[108:111], v[140:143], v[168:171], v[108:111]
	v_mfma_f32_16x16x32_bf16 v[104:107], v[148:151], v[168:171], v[104:107]
	v_mfma_f32_16x16x32_bf16 v[92:95], v[140:143], v[176:179], v[92:95]
	v_mfma_f32_16x16x32_bf16 v[88:91], v[148:151], v[176:179], v[88:91]
	v_mfma_f32_16x16x32_bf16 v[76:79], v[140:143], v[184:187], v[76:79]
	v_mfma_f32_16x16x32_bf16 v[72:75], v[148:151], v[184:187], v[72:75]
	v_mfma_f32_16x16x32_bf16 v[116:119], v[188:191], v[156:159], v[116:119]
	v_mfma_f32_16x16x32_bf16 v[112:115], v[196:199], v[156:159], v[112:115]
	v_mfma_f32_16x16x32_bf16 v[100:103], v[188:191], v[164:167], v[100:103]
	v_mfma_f32_16x16x32_bf16 v[96:99], v[196:199], v[164:167], v[96:99]
	v_mfma_f32_16x16x32_bf16 v[84:87], v[188:191], v[172:175], v[84:87]
	v_mfma_f32_16x16x32_bf16 v[80:83], v[196:199], v[172:175], v[80:83]
	v_mfma_f32_16x16x32_bf16 v[68:71], v[188:191], v[180:183], v[68:71]
	v_mfma_f32_16x16x32_bf16 v[64:67], v[196:199], v[180:183], v[64:67]
	v_mfma_f32_16x16x32_bf16 v[116:119], v[192:195], v[160:163], v[116:119]
	v_mfma_f32_16x16x32_bf16 v[112:115], v[200:203], v[160:163], v[112:115]
	v_mfma_f32_16x16x32_bf16 v[100:103], v[192:195], v[168:171], v[100:103]
	v_mfma_f32_16x16x32_bf16 v[96:99], v[200:203], v[168:171], v[96:99]
	v_mfma_f32_16x16x32_bf16 v[84:87], v[192:195], v[176:179], v[84:87]
	v_mfma_f32_16x16x32_bf16 v[80:83], v[200:203], v[176:179], v[80:83]
	v_mfma_f32_16x16x32_bf16 v[68:71], v[192:195], v[184:187], v[68:71]
	v_mfma_f32_16x16x32_bf16 v[64:67], v[200:203], v[184:187], v[64:67]
	s_barrier
	s_mov_b32 m0, s55
	v_lshl_add_u64 v[204:205], s[28:29], 0, v[128:129]
	global_load_lds_dwordx4 v[204:205], off
	s_add_i32 m0, s55, 0x2000
	v_lshl_add_u64 v[204:205], s[28:29], 0, v[130:131]
	global_load_lds_dwordx4 v[204:205], off
	s_mov_b32 m0, s43
	v_lshl_add_u64 v[204:205], s[26:27], 0, v[128:129]
	global_load_lds_dwordx4 v[204:205], off
	s_mov_b32 m0, s44
	v_lshl_add_u64 v[204:205], s[26:27], 0, v[130:131]
	global_load_lds_dwordx4 v[204:205], off
	s_add_u32 s24, s24, 0x84000
	s_addc_u32 s25, s25, 0
	s_add_i32 s26, s56, s36
	s_mov_b32 m0, s26
	v_lshl_add_u64 v[204:205], s[24:25], 0, v[128:129]
	global_load_lds_dwordx4 v[204:205], off
	s_add_i32 m0, s26, 0x2000
	v_lshl_add_u64 v[204:205], s[24:25], 0, v[130:131]
	global_load_lds_dwordx4 v[204:205], off
	ds_read_b128 v[156:159], v135 offset:49152
	ds_read_b128 v[164:167], v135 offset:51200
	ds_read_b128 v[172:175], v135 offset:53248
	ds_read_b128 v[180:183], v135 offset:55296
	ds_read_b128 v[160:163], v135 offset:50176
	ds_read_b128 v[168:171], v135 offset:52224
	ds_read_b128 v[176:179], v135 offset:54272
	ds_read_b128 v[184:187], v135 offset:56320
	s_waitcnt vmcnt(6)
	s_waitcnt lgkmcnt(0)
	s_barrier
	v_mfma_f32_16x16x32_bf16 v[60:63], v[136:139], v[156:159], v[60:63]
	v_mfma_f32_16x16x32_bf16 v[56:59], v[144:147], v[156:159], v[56:59]
	v_mfma_f32_16x16x32_bf16 v[44:47], v[136:139], v[164:167], v[44:47]
	v_mfma_f32_16x16x32_bf16 v[40:43], v[144:147], v[164:167], v[40:43]
	v_mfma_f32_16x16x32_bf16 v[28:31], v[136:139], v[172:175], v[28:31]
	v_mfma_f32_16x16x32_bf16 v[24:27], v[144:147], v[172:175], v[24:27]
	v_mfma_f32_16x16x32_bf16 v[12:15], v[136:139], v[180:183], v[12:15]
	v_mfma_f32_16x16x32_bf16 v[8:11], v[144:147], v[180:183], v[8:11]
	v_mfma_f32_16x16x32_bf16 v[60:63], v[140:143], v[160:163], v[60:63]
	v_mfma_f32_16x16x32_bf16 v[56:59], v[148:151], v[160:163], v[56:59]
	v_mfma_f32_16x16x32_bf16 v[44:47], v[140:143], v[168:171], v[44:47]
	v_mfma_f32_16x16x32_bf16 v[40:43], v[148:151], v[168:171], v[40:43]
	v_mfma_f32_16x16x32_bf16 v[28:31], v[140:143], v[176:179], v[28:31]
	v_mfma_f32_16x16x32_bf16 v[24:27], v[148:151], v[176:179], v[24:27]
	v_mfma_f32_16x16x32_bf16 v[12:15], v[140:143], v[184:187], v[12:15]
	v_mfma_f32_16x16x32_bf16 v[8:11], v[148:151], v[184:187], v[8:11]
	v_mfma_f32_16x16x32_bf16 v[52:55], v[188:191], v[156:159], v[52:55]
	v_mfma_f32_16x16x32_bf16 v[48:51], v[196:199], v[156:159], v[48:51]
	s_add_i32 s54, s54, 2
	s_add_u32 s22, s22, 0x8000
	s_addc_u32 s23, s23, 0
	s_add_u32 s51, s51, 0x8000
	s_addc_u32 s52, s52, 0
	v_mfma_f32_16x16x32_bf16 v[36:39], v[188:191], v[164:167], v[36:39]
	v_mfma_f32_16x16x32_bf16 v[32:35], v[196:199], v[164:167], v[32:35]
	v_mfma_f32_16x16x32_bf16 v[20:23], v[188:191], v[172:175], v[20:23]
	v_mfma_f32_16x16x32_bf16 v[16:19], v[196:199], v[172:175], v[16:19]
	v_mfma_f32_16x16x32_bf16 v[4:7], v[188:191], v[180:183], v[4:7]
	v_mfma_f32_16x16x32_bf16 v[0:3], v[196:199], v[180:183], v[0:3]
	v_mfma_f32_16x16x32_bf16 v[52:55], v[192:195], v[160:163], v[52:55]
	v_mfma_f32_16x16x32_bf16 v[48:51], v[200:203], v[160:163], v[48:51]
	v_mfma_f32_16x16x32_bf16 v[36:39], v[192:195], v[168:171], v[36:39]
	v_mfma_f32_16x16x32_bf16 v[32:35], v[200:203], v[168:171], v[32:35]
	v_mfma_f32_16x16x32_bf16 v[20:23], v[192:195], v[176:179], v[20:23]
	v_mfma_f32_16x16x32_bf16 v[16:19], v[200:203], v[176:179], v[16:19]
	v_mfma_f32_16x16x32_bf16 v[4:7], v[192:195], v[184:187], v[4:7]
	s_cmp_gt_u32 s54, 29
	v_mfma_f32_16x16x32_bf16 v[0:3], v[200:203], v[184:187], v[0:3]
	s_barrier
	s_cbranch_scc0 .LBB0_141

; #define PG8_STAGE(bufoff, gbase, voff) do { _Pragma("unroll") for (int _i = 0; _i < 2; ++_i) \
;         __builtin_amdgcn_global_load_lds((const unsigned*)((const char*)(gbase) + (voff)[_i]), (LAS unsigned*)(lds + (bufoff) + ldsw + _i * 8192), 16, 0, 0); } while (0)
; #define PG8_LDA(dst, b, h) do { _Pragma("unroll") for (int m = 0; m < 4; ++m) _Pragma("unroll") for (int k = 0; k < 2; ++k) dst[m][k] = *(const LAS bf16x8*)(lds + PG8_SA(b, h) + aoff + m * 2048 + k * 1024); } while (0)
; #define PG8_LDB(dst, b, h) do { _Pragma("unroll") for (int n = 0; n < 2; ++n) _Pragma("unroll") for (int k = 0; k < 2; ++k) dst[n][k] = *(const LAS bf16x8*)(lds + PG8_SB(b, h) + boff + n * 2048 + k * 1024); } while (0)
; #define PG8_WAIT_V(n) asm volatile("s_waitcnt vmcnt(" #n ")" ::: "memory")
; #define PG8_WAIT_L(n) asm volatile("s_waitcnt lgkmcnt(" #n ")" ::: "memory")
; #define PG8_BAR __builtin_amdgcn_s_barrier()
; #define PG8_SCHED __builtin_amdgcn_sched_barrier(0)
; template <class Epi>
; __device__ __forceinline__ void gemm_phase(LAS unsigned char* lds, const Gemm g, const StaticOrder& S, const Epi& E) {
;     ...
;         const bool has_next = S.next(ui + 1, nxt);
;         const char* nA = has_next ? (const char*)g.A + (size_t)nxt.pm * tstepA : cA; const char* nB = has_next ? (const char*)g.Bt + (size_t)nxt.pn * tstepB : cB;
;         for (int t = 0; t < nt; t += 2) {
;             const bool last = (t == nt - 2);
;             const char* a1 = cA + (size_t)(t + 1) * kstep;
;             const char* a2 = last ? nA : cA + (size_t)(t + 2) * kstep; const char* b2 = last ? nB : cB + (size_t)(t + 2) * kstep;
;             const char* a3 = a2 + kstep; const char* b3 = b2 + kstep;
;             PG8_LDB(B0, 0, 0); PG8_SCHED; PG8_LDA(At, 0, 0); PG8_STAGE(PG8_SA(1, 1), a1 + hstepA, voffA);
;             PG8_WAIT_L(8); PG8_BAR; PG8_WAIT_L(0); PG8_MMA(0, 0, At, B0); PG8_BAR; PG8_SCHED;
;             PG8_LDB(B1, 0, 1); PG8_STAGE(PG8_SB(0, 0), b2, voffB);
;             PG8_BAR; PG8_WAIT_L(0); PG8_MMA(0, 1, At, B1); PG8_BAR;
;             PG8_LDA(At, 0, 1); PG8_STAGE(PG8_SA(0, 0), a2, voffA);
;             PG8_BAR; PG8_WAIT_L(0); PG8_MMA(1, 0, At, B0); PG8_BAR; PG8_SCHED;
;             PG8_STAGE(PG8_SB(0, 1), b2 + hstepB, voffB);
;             PG8_WAIT_V(6); PG8_BAR; PG8_MMA(1, 1, At, B1); PG8_BAR;
.LBB0_186:
	s_add_u32 s4, s24, 0x4000
	s_addc_u32 s5, s25, 0
	s_add_u32 s50, s22, 0x8000
	s_addc_u32 s51, s23, 0
	s_mov_b32 s22, 0
	s_add_i32 s54, s22, 2
	s_add_u32 s23, s4, 0x4000
	s_addc_u32 s24, s5, 0
	s_cmp_eq_u32 s40, s22
	s_cselect_b32 s26, s6, s23
	s_cselect_b32 s27, s7, s24
	s_cselect_b32 s24, s20, s50
	s_cselect_b32 s25, s21, s51
	s_add_u32 s22, s26, 0x4000
	s_addc_u32 s23, s27, 0
	s_add_i32 m0, s33, 0xc000
	v_lshl_add_u64 v[186:187], s[4:5], 0, v[158:159]
	global_load_lds_dwordx4 v[186:187], off
	s_add_i32 m0, s33, 0xe000
	v_lshl_add_u64 v[186:187], s[4:5], 0, v[160:161]
	global_load_lds_dwordx4 v[186:187], off
	s_mov_b32 s55, 0x10000
	v_add_u32_e32 v140, s55, v207
	ds_read_b128 v[128:131], v140
	ds_read_b128 v[136:139], v140 offset:2048
	ds_read_b128 v[132:135], v140 offset:1024
	ds_read_b128 v[140:143], v140 offset:3072
	ds_read_b128 v[144:147], v209
	ds_read_b128 v[162:165], v209 offset:2048
	ds_read_b128 v[170:173], v209 offset:4096
	ds_read_b128 v[178:181], v209 offset:6144
	ds_read_b128 v[148:151], v209 offset:1024
	ds_read_b128 v[166:169], v209 offset:3072
	ds_read_b128 v[174:177], v209 offset:5120
	ds_read_b128 v[182:185], v209 offset:7168
	s_mov_b32 s58, 0x14000
	s_add_i32 s55, s55, s31
	v_add_u32_e32 v198, s58, v207
	ds_read_b128 v[186:189], v198
	ds_read_b128 v[194:197], v198 offset:2048
	ds_read_b128 v[190:193], v198 offset:1024
	ds_read_b128 v[198:201], v198 offset:3072
	s_waitcnt lgkmcnt(0)
	s_barrier
	v_mfma_f32_16x16x32_bf16 v[124:127], v[128:131], v[144:147], 0
	v_mfma_f32_16x16x32_bf16 v[120:123], v[136:139], v[144:147], 0
	v_mfma_f32_16x16x32_bf16 v[116:119], v[128:131], v[162:165], 0
	v_mfma_f32_16x16x32_bf16 v[112:115], v[136:139], v[162:165], 0
	v_mfma_f32_16x16x32_bf16 v[108:111], v[128:131], v[170:173], 0
	v_mfma_f32_16x16x32_bf16 v[104:107], v[136:139], v[170:173], 0
	v_mfma_f32_16x16x32_bf16 v[100:103], v[128:131], v[178:181], 0
	v_mfma_f32_16x16x32_bf16 v[96:99], v[136:139], v[178:181], 0
	v_mfma_f32_16x16x32_bf16 v[124:127], v[132:135], v[148:151], v[124:127]
	v_mfma_f32_16x16x32_bf16 v[120:123], v[140:143], v[148:151], v[120:123]
	v_mfma_f32_16x16x32_bf16 v[116:119], v[132:135], v[166:169], v[116:119]
	v_mfma_f32_16x16x32_bf16 v[112:115], v[140:143], v[166:169], v[112:115]
	v_mfma_f32_16x16x32_bf16 v[108:111], v[132:135], v[174:177], v[108:111]
	v_mfma_f32_16x16x32_bf16 v[104:107], v[140:143], v[174:177], v[104:107]
	v_mfma_f32_16x16x32_bf16 v[100:103], v[132:135], v[182:185], v[100:103]
	v_mfma_f32_16x16x32_bf16 v[96:99], v[140:143], v[182:185], v[96:99]
	v_mfma_f32_16x16x32_bf16 v[92:95], v[186:189], v[144:147], 0
	v_mfma_f32_16x16x32_bf16 v[88:91], v[194:197], v[144:147], 0
	v_mfma_f32_16x16x32_bf16 v[84:87], v[186:189], v[162:165], 0
	v_mfma_f32_16x16x32_bf16 v[80:83], v[194:197], v[162:165], 0
	v_mfma_f32_16x16x32_bf16 v[76:79], v[186:189], v[170:173], 0
	v_mfma_f32_16x16x32_bf16 v[72:75], v[194:197], v[170:173], 0
	v_mfma_f32_16x16x32_bf16 v[68:71], v[186:189], v[178:181], 0
	v_mfma_f32_16x16x32_bf16 v[64:67], v[194:197], v[178:181], 0
	v_mfma_f32_16x16x32_bf16 v[92:95], v[190:193], v[148:151], v[92:95]
	v_mfma_f32_16x16x32_bf16 v[88:91], v[198:201], v[148:151], v[88:91]
	v_mfma_f32_16x16x32_bf16 v[84:87], v[190:193], v[166:169], v[84:87]
	v_mfma_f32_16x16x32_bf16 v[80:83], v[198:201], v[166:169], v[80:83]
	v_mfma_f32_16x16x32_bf16 v[76:79], v[190:193], v[174:177], v[76:79]
	v_mfma_f32_16x16x32_bf16 v[72:75], v[198:201], v[174:177], v[72:75]
	v_mfma_f32_16x16x32_bf16 v[68:71], v[190:193], v[182:185], v[68:71]
	v_mfma_f32_16x16x32_bf16 v[64:67], v[198:201], v[182:185], v[64:67]
	s_barrier
	s_mov_b32 m0, s55
	v_lshl_add_u64 v[202:203], s[24:25], 0, v[152:153]
	global_load_lds_dwordx4 v[202:203], off
	s_add_i32 m0, s55, 0x2000
	v_lshl_add_u64 v[202:203], s[24:25], 0, v[156:157]
	global_load_lds_dwordx4 v[202:203], off
	s_mov_b32 m0, s33
	v_lshl_add_u64 v[202:203], s[26:27], 0, v[152:153]
	global_load_lds_dwordx4 v[202:203], off
	s_mov_b32 m0, s34
	v_lshl_add_u64 v[202:203], s[26:27], 0, v[156:157]
	global_load_lds_dwordx4 v[202:203], off
	s_add_u32 s56, s24, s52
	s_addc_u32 s57, s25, 0
	s_add_i32 s55, s58, s31
	s_mov_b32 m0, s55
	v_lshl_add_u64 v[202:203], s[56:57], 0, v[152:153]
	global_load_lds_dwordx4 v[202:203], off
	s_add_i32 m0, s55, 0x2000
	v_lshl_add_u64 v[202:203], s[56:57], 0, v[156:157]
	global_load_lds_dwordx4 v[202:203], off
	ds_read_b128 v[144:147], v209 offset:16384
	ds_read_b128 v[162:165], v209 offset:18432
	ds_read_b128 v[170:173], v209 offset:20480
	ds_read_b128 v[178:181], v209 offset:22528
	ds_read_b128 v[148:151], v209 offset:17408
	ds_read_b128 v[166:169], v209 offset:19456
	ds_read_b128 v[174:177], v209 offset:21504
	ds_read_b128 v[182:185], v209 offset:23552
	s_waitcnt vmcnt(6)
	s_waitcnt lgkmcnt(0)
	s_barrier
; #define PG8_STAGE(bufoff, gbase, voff) do { _Pragma("unroll") for (int _i = 0; _i < 2; ++_i) \
;         __builtin_amdgcn_global_load_lds((const unsigned*)((const char*)(gbase) + (voff)[_i]), (LAS unsigned*)(lds + (bufoff) + ldsw + _i * 8192), 16, 0, 0); } while (0)
; #define PG8_LDA(dst, b, h) do { _Pragma("unroll") for (int m = 0; m < 4; ++m) _Pragma("unroll") for (int k = 0; k < 2; ++k) dst[m][k] = *(const LAS bf16x8*)(lds + PG8_SA(b, h) + aoff + m * 2048 + k * 1024); } while (0)
; #define PG8_LDB(dst, b, h) do { _Pragma("unroll") for (int n = 0; n < 2; ++n) _Pragma("unroll") for (int k = 0; k < 2; ++k) dst[n][k] = *(const LAS bf16x8*)(lds + PG8_SB(b, h) + boff + n * 2048 + k * 1024); } while (0)
; #define PG8_MMA(ai, bj, At, Bt) do { __builtin_amdgcn_s_setprio(1); _Pragma("unroll") for (int m = 0; m < 4; ++m) _Pragma("unroll") for (int n = 0; n < 2; ++n) _Pragma("unroll") for (int k = 0; k < 2; ++k) \
;         acc[ai][bj][m][n] = __builtin_amdgcn_mfma_f32_16x16x32_bf16(Bt[n][k], At[m][k], acc[ai][bj][m][n], 0, 0, 0); __builtin_amdgcn_s_setprio(0); } while (0)
; #define PG8_WAIT_V(n) asm volatile("s_waitcnt vmcnt(" #n ")" ::: "memory")
; #define PG8_WAIT_L(n) asm volatile("s_waitcnt lgkmcnt(" #n ")" ::: "memory")
; #define PG8_BAR __builtin_amdgcn_s_barrier()
; #define PG8_SCHED __builtin_amdgcn_sched_barrier(0)
; template <class Epi>
; __device__ __forceinline__ void gemm_phase(LAS unsigned char* lds, const Gemm g, const StaticOrder& S, const Epi& E) {
;     ...
;             PG8_WAIT_V(6); PG8_BAR; PG8_MMA(1, 1, At, B1); PG8_BAR;
;             PG8_LDB(B0, 1, 0); PG8_SCHED; PG8_LDA(At, 1, 0); PG8_STAGE(PG8_SA(0, 1), a2 + hstepA, voffA);
;             PG8_WAIT_L(8); PG8_BAR; PG8_WAIT_L(0); PG8_MMA(0, 0, At, B0); PG8_BAR; PG8_SCHED;
;             PG8_LDB(B1, 1, 1); PG8_STAGE(PG8_SB(1, 0), b3, voffB);
;             PG8_BAR; PG8_WAIT_L(0); PG8_MMA(0, 1, At, B1); PG8_BAR;
;             PG8_LDA(At, 1, 1); PG8_STAGE(PG8_SA(1, 0), a3, voffA);
;             PG8_BAR; PG8_WAIT_L(0); PG8_MMA(1, 0, At, B0); PG8_BAR; PG8_SCHED;
	v_mfma_f32_16x16x32_bf16 v[60:63], v[128:131], v[144:147], 0
	v_mfma_f32_16x16x32_bf16 v[56:59], v[136:139], v[144:147], 0
	v_mfma_f32_16x16x32_bf16 v[52:55], v[128:131], v[162:165], 0
	v_mfma_f32_16x16x32_bf16 v[48:51], v[136:139], v[162:165], 0
	v_mfma_f32_16x16x32_bf16 v[44:47], v[128:131], v[170:173], 0
	v_mfma_f32_16x16x32_bf16 v[40:43], v[136:139], v[170:173], 0
	v_mfma_f32_16x16x32_bf16 v[36:39], v[128:131], v[178:181], 0
	v_mfma_f32_16x16x32_bf16 v[32:35], v[136:139], v[178:181], 0
	v_mfma_f32_16x16x32_bf16 v[60:63], v[132:135], v[148:151], v[60:63]
	v_mfma_f32_16x16x32_bf16 v[56:59], v[140:143], v[148:151], v[56:59]
	v_mfma_f32_16x16x32_bf16 v[52:55], v[132:135], v[166:169], v[52:55]
	v_mfma_f32_16x16x32_bf16 v[48:51], v[140:143], v[166:169], v[48:51]
	v_mfma_f32_16x16x32_bf16 v[44:47], v[132:135], v[174:177], v[44:47]
	v_mfma_f32_16x16x32_bf16 v[40:43], v[140:143], v[174:177], v[40:43]
	v_mfma_f32_16x16x32_bf16 v[36:39], v[132:135], v[182:185], v[36:39]
	v_mfma_f32_16x16x32_bf16 v[32:35], v[140:143], v[182:185], v[32:35]
	v_mfma_f32_16x16x32_bf16 v[28:31], v[186:189], v[144:147], 0
	v_mfma_f32_16x16x32_bf16 v[24:27], v[194:197], v[144:147], 0
	s_add_i32 s55, 0, 0x18000
	v_add_u32_e32 v140, s55, v207
	v_mfma_f32_16x16x32_bf16 v[20:23], v[186:189], v[162:165], 0
	v_mfma_f32_16x16x32_bf16 v[16:19], v[194:197], v[162:165], 0
	v_mfma_f32_16x16x32_bf16 v[12:15], v[186:189], v[170:173], 0
	v_mfma_f32_16x16x32_bf16 v[8:11], v[194:197], v[170:173], 0
	v_mfma_f32_16x16x32_bf16 v[4:7], v[186:189], v[178:181], 0
	v_mfma_f32_16x16x32_bf16 v[0:3], v[194:197], v[178:181], 0
	v_mfma_f32_16x16x32_bf16 v[28:31], v[190:193], v[148:151], v[28:31]
	v_mfma_f32_16x16x32_bf16 v[24:27], v[198:201], v[148:151], v[24:27]
	v_mfma_f32_16x16x32_bf16 v[20:23], v[190:193], v[166:169], v[20:23]
	v_mfma_f32_16x16x32_bf16 v[16:19], v[198:201], v[166:169], v[16:19]
	v_mfma_f32_16x16x32_bf16 v[12:15], v[190:193], v[174:177], v[12:15]
	v_mfma_f32_16x16x32_bf16 v[8:11], v[198:201], v[174:177], v[8:11]
	v_mfma_f32_16x16x32_bf16 v[4:7], v[190:193], v[182:185], v[4:7]
	v_mfma_f32_16x16x32_bf16 v[0:3], v[198:201], v[182:185], v[0:3]
	s_barrier
	s_add_u32 s26, s26, s52
	s_addc_u32 s27, s27, 0
	s_mov_b32 m0, s35
	v_lshl_add_u64 v[186:187], s[26:27], 0, v[152:153]
	global_load_lds_dwordx4 v[186:187], off
	s_mov_b32 m0, s36
	v_lshl_add_u64 v[186:187], s[26:27], 0, v[156:157]
	global_load_lds_dwordx4 v[186:187], off
	ds_read_b128 v[128:131], v140
	ds_read_b128 v[136:139], v140 offset:2048
	ds_read_b128 v[132:135], v140 offset:1024
	ds_read_b128 v[140:143], v140 offset:3072
	ds_read_b128 v[144:147], v209 offset:32768
	ds_read_b128 v[162:165], v209 offset:34816
	ds_read_b128 v[170:173], v209 offset:36864
	ds_read_b128 v[178:181], v209 offset:38912
	ds_read_b128 v[148:151], v209 offset:33792
	ds_read_b128 v[166:169], v209 offset:35840
	ds_read_b128 v[174:177], v209 offset:37888
	ds_read_b128 v[182:185], v209 offset:39936
	s_mov_b32 s26, 0x1c000
	s_add_u32 s24, s24, 0x4000
	s_addc_u32 s25, s25, 0
	s_add_i32 s27, s55, s31
	v_add_u32_e32 v198, s26, v207
	ds_read_b128 v[186:189], v198
	ds_read_b128 v[194:197], v198 offset:2048
	ds_read_b128 v[190:193], v198 offset:1024
	ds_read_b128 v[198:201], v198 offset:3072
	s_waitcnt lgkmcnt(0)
	s_barrier
	v_mfma_f32_16x16x32_bf16 v[124:127], v[128:131], v[144:147], v[124:127]
	v_mfma_f32_16x16x32_bf16 v[120:123], v[136:139], v[144:147], v[120:123]
	v_mfma_f32_16x16x32_bf16 v[116:119], v[128:131], v[162:165], v[116:119]
	v_mfma_f32_16x16x32_bf16 v[112:115], v[136:139], v[162:165], v[112:115]
	v_mfma_f32_16x16x32_bf16 v[108:111], v[128:131], v[170:173], v[108:111]
	v_mfma_f32_16x16x32_bf16 v[104:107], v[136:139], v[170:173], v[104:107]
	v_mfma_f32_16x16x32_bf16 v[100:103], v[128:131], v[178:181], v[100:103]
	v_mfma_f32_16x16x32_bf16 v[96:99], v[136:139], v[178:181], v[96:99]
	v_mfma_f32_16x16x32_bf16 v[124:127], v[132:135], v[148:151], v[124:127]
	v_mfma_f32_16x16x32_bf16 v[120:123], v[140:143], v[148:151], v[120:123]
	v_mfma_f32_16x16x32_bf16 v[116:119], v[132:135], v[166:169], v[116:119]
	v_mfma_f32_16x16x32_bf16 v[112:115], v[140:143], v[166:169], v[112:115]
	v_mfma_f32_16x16x32_bf16 v[108:111], v[132:135], v[174:177], v[108:111]
	v_mfma_f32_16x16x32_bf16 v[104:107], v[140:143], v[174:177], v[104:107]
	v_mfma_f32_16x16x32_bf16 v[100:103], v[132:135], v[182:185], v[100:103]
	v_mfma_f32_16x16x32_bf16 v[96:99], v[140:143], v[182:185], v[96:99]
	v_mfma_f32_16x16x32_bf16 v[92:95], v[186:189], v[144:147], v[92:95]
	v_mfma_f32_16x16x32_bf16 v[88:91], v[194:197], v[144:147], v[88:91]
	v_mfma_f32_16x16x32_bf16 v[84:87], v[186:189], v[162:165], v[84:87]
	v_mfma_f32_16x16x32_bf16 v[80:83], v[194:197], v[162:165], v[80:83]
	v_mfma_f32_16x16x32_bf16 v[76:79], v[186:189], v[170:173], v[76:79]
	v_mfma_f32_16x16x32_bf16 v[72:75], v[194:197], v[170:173], v[72:75]
	v_mfma_f32_16x16x32_bf16 v[68:71], v[186:189], v[178:181], v[68:71]
	v_mfma_f32_16x16x32_bf16 v[64:67], v[194:197], v[178:181], v[64:67]
	v_mfma_f32_16x16x32_bf16 v[92:95], v[190:193], v[148:151], v[92:95]
	v_mfma_f32_16x16x32_bf16 v[88:91], v[198:201], v[148:151], v[88:91]
	v_mfma_f32_16x16x32_bf16 v[84:87], v[190:193], v[166:169], v[84:87]
	v_mfma_f32_16x16x32_bf16 v[80:83], v[198:201], v[166:169], v[80:83]
	v_mfma_f32_16x16x32_bf16 v[76:79], v[190:193], v[174:177], v[76:79]
	v_mfma_f32_16x16x32_bf16 v[72:75], v[198:201], v[174:177], v[72:75]
	v_mfma_f32_16x16x32_bf16 v[68:71], v[190:193], v[182:185], v[68:71]
	v_mfma_f32_16x16x32_bf16 v[64:67], v[198:201], v[182:185], v[64:67]
	s_barrier
; #define PG8_STAGE(bufoff, gbase, voff) do { _Pragma("unroll") for (int _i = 0; _i < 2; ++_i) \
;         __builtin_amdgcn_global_load_lds((const unsigned*)((const char*)(gbase) + (voff)[_i]), (LAS unsigned*)(lds + (bufoff) + ldsw + _i * 8192), 16, 0, 0); } while (0)
; #define PG8_LDA(dst, b, h) do { _Pragma("unroll") for (int m = 0; m < 4; ++m) _Pragma("unroll") for (int k = 0; k < 2; ++k) dst[m][k] = *(const LAS bf16x8*)(lds + PG8_SA(b, h) + aoff + m * 2048 + k * 1024); } while (0)
; #define PG8_LDB(dst, b, h) do { _Pragma("unroll") for (int n = 0; n < 2; ++n) _Pragma("unroll") for (int k = 0; k < 2; ++k) dst[n][k] = *(const LAS bf16x8*)(lds + PG8_SB(b, h) + boff + n * 2048 + k * 1024); } while (0)
; #define PG8_MMA(ai, bj, At, Bt) do { __builtin_amdgcn_s_setprio(1); _Pragma("unroll") for (int m = 0; m < 4; ++m) _Pragma("unroll") for (int n = 0; n < 2; ++n) _Pragma("unroll") for (int k = 0; k < 2; ++k) \
;         acc[ai][bj][m][n] = __builtin_amdgcn_mfma_f32_16x16x32_bf16(Bt[n][k], At[m][k], acc[ai][bj][m][n], 0, 0, 0); __builtin_amdgcn_s_setprio(0); } while (0)
; #define PG8_WAIT_V(n) asm volatile("s_waitcnt vmcnt(" #n ")" ::: "memory")
; #define PG8_WAIT_L(n) asm volatile("s_waitcnt lgkmcnt(" #n ")" ::: "memory")
; #define PG8_BAR __builtin_amdgcn_s_barrier()
; #define PG8_SCHED __builtin_amdgcn_sched_barrier(0)
; template <class Epi>
; __device__ __forceinline__ void gemm_phase(LAS unsigned char* lds, const Gemm g, const StaticOrder& S, const Epi& E) {
;     ...
;         for (int t = 0; t < nt; t += 2) {
;             const bool last = (t == nt - 2);
;             const char* a1 = cA + (size_t)(t + 1) * kstep;
;             const char* a2 = last ? nA : cA + (size_t)(t + 2) * kstep; const char* b2 = last ? nB : cB + (size_t)(t + 2) * kstep;
;             const char* a3 = a2 + kstep; const char* b3 = b2 + kstep;
;             PG8_LDB(B0, 0, 0); PG8_SCHED; PG8_LDA(At, 0, 0); PG8_STAGE(PG8_SA(1, 1), a1 + hstepA, voffA);
;             PG8_WAIT_L(8); PG8_BAR; PG8_WAIT_L(0); PG8_MMA(0, 0, At, B0); PG8_BAR; PG8_SCHED;
;     ...
;             PG8_BAR; PG8_WAIT_L(0); PG8_MMA(0, 1, At, B1); PG8_BAR;
;             PG8_LDA(At, 1, 1); PG8_STAGE(PG8_SA(1, 0), a3, voffA);
;             PG8_BAR; PG8_WAIT_L(0); PG8_MMA(1, 0, At, B0); PG8_BAR; PG8_SCHED;
;             PG8_STAGE(PG8_SB(1, 1), b3 + hstepB, voffB);
;             PG8_WAIT_V(6); PG8_BAR; PG8_MMA(1, 1, At, B1); PG8_BAR;
	s_mov_b32 m0, s27
	v_lshl_add_u64 v[202:203], s[24:25], 0, v[152:153]
	global_load_lds_dwordx4 v[202:203], off
	s_add_i32 m0, s27, 0x2000
	v_lshl_add_u64 v[202:203], s[24:25], 0, v[156:157]
	global_load_lds_dwordx4 v[202:203], off
	s_mov_b32 m0, s38
	v_lshl_add_u64 v[202:203], s[22:23], 0, v[152:153]
	global_load_lds_dwordx4 v[202:203], off
	s_mov_b32 m0, s39
	v_lshl_add_u64 v[202:203], s[22:23], 0, v[156:157]
	global_load_lds_dwordx4 v[202:203], off
	s_add_u32 s22, s24, s52
	s_addc_u32 s23, s25, 0
	s_add_i32 s24, s26, s31
	s_mov_b32 m0, s24
	v_lshl_add_u64 v[202:203], s[22:23], 0, v[152:153]
	global_load_lds_dwordx4 v[202:203], off
	s_add_i32 m0, s24, 0x2000
	v_lshl_add_u64 v[202:203], s[22:23], 0, v[156:157]
	global_load_lds_dwordx4 v[202:203], off
	ds_read_b128 v[144:147], v209 offset:49152
	ds_read_b128 v[162:165], v209 offset:51200
	ds_read_b128 v[170:173], v209 offset:53248
	ds_read_b128 v[178:181], v209 offset:55296
	ds_read_b128 v[148:151], v209 offset:50176
	ds_read_b128 v[166:169], v209 offset:52224
	ds_read_b128 v[174:177], v209 offset:54272
	ds_read_b128 v[182:185], v209 offset:56320
	s_waitcnt vmcnt(6)
	s_waitcnt lgkmcnt(0)
	s_barrier
	v_mfma_f32_16x16x32_bf16 v[60:63], v[128:131], v[144:147], v[60:63]
	v_mfma_f32_16x16x32_bf16 v[56:59], v[136:139], v[144:147], v[56:59]
	v_mfma_f32_16x16x32_bf16 v[52:55], v[128:131], v[162:165], v[52:55]
	v_mfma_f32_16x16x32_bf16 v[48:51], v[136:139], v[162:165], v[48:51]
	v_mfma_f32_16x16x32_bf16 v[44:47], v[128:131], v[170:173], v[44:47]
	v_mfma_f32_16x16x32_bf16 v[40:43], v[136:139], v[170:173], v[40:43]
	v_mfma_f32_16x16x32_bf16 v[36:39], v[128:131], v[178:181], v[36:39]
	v_mfma_f32_16x16x32_bf16 v[32:35], v[136:139], v[178:181], v[32:35]
	v_mfma_f32_16x16x32_bf16 v[60:63], v[132:135], v[148:151], v[60:63]
	v_mfma_f32_16x16x32_bf16 v[56:59], v[140:143], v[148:151], v[56:59]
	v_mfma_f32_16x16x32_bf16 v[52:55], v[132:135], v[166:169], v[52:55]
	v_mfma_f32_16x16x32_bf16 v[48:51], v[140:143], v[166:169], v[48:51]
	v_mfma_f32_16x16x32_bf16 v[44:47], v[132:135], v[174:177], v[44:47]
	v_mfma_f32_16x16x32_bf16 v[40:43], v[140:143], v[174:177], v[40:43]
	v_mfma_f32_16x16x32_bf16 v[36:39], v[132:135], v[182:185], v[36:39]
	v_mfma_f32_16x16x32_bf16 v[32:35], v[140:143], v[182:185], v[32:35]
	v_mfma_f32_16x16x32_bf16 v[28:31], v[186:189], v[144:147], v[28:31]
	v_mfma_f32_16x16x32_bf16 v[24:27], v[194:197], v[144:147], v[24:27]
	s_add_u32 s4, s4, 0x8000
	s_addc_u32 s5, s5, 0
	s_add_u32 s50, s50, 0x8000
	s_addc_u32 s51, s51, 0
	v_mfma_f32_16x16x32_bf16 v[20:23], v[186:189], v[162:165], v[20:23]
	v_mfma_f32_16x16x32_bf16 v[16:19], v[194:197], v[162:165], v[16:19]
	v_mfma_f32_16x16x32_bf16 v[12:15], v[186:189], v[170:173], v[12:15]
	v_mfma_f32_16x16x32_bf16 v[8:11], v[194:197], v[170:173], v[8:11]
	v_mfma_f32_16x16x32_bf16 v[4:7], v[186:189], v[178:181], v[4:7]
	v_mfma_f32_16x16x32_bf16 v[0:3], v[194:197], v[178:181], v[0:3]
	v_mfma_f32_16x16x32_bf16 v[28:31], v[190:193], v[148:151], v[28:31]
	v_mfma_f32_16x16x32_bf16 v[24:27], v[198:201], v[148:151], v[24:27]
	v_mfma_f32_16x16x32_bf16 v[20:23], v[190:193], v[166:169], v[20:23]
	v_mfma_f32_16x16x32_bf16 v[16:19], v[198:201], v[166:169], v[16:19]
	v_mfma_f32_16x16x32_bf16 v[12:15], v[190:193], v[174:177], v[12:15]
	v_mfma_f32_16x16x32_bf16 v[8:11], v[198:201], v[174:177], v[8:11]
	v_mfma_f32_16x16x32_bf16 v[4:7], v[190:193], v[182:185], v[4:7]
	s_cmp_ge_u32 s54, s28
	s_mov_b32 s22, s54
	v_mfma_f32_16x16x32_bf16 v[0:3], v[198:201], v[182:185], v[0:3]
	s_barrier
	s_cbranch_scc0 .LBB0_187
	s_branch .Lpeel_done_187
.LBB0_187:
	s_add_i32 s54, s22, 2
	s_add_u32 s23, s4, 0x4000
	s_addc_u32 s24, s5, 0
	s_cmp_eq_u32 s40, s22
	s_cselect_b32 s26, s6, s23
	s_cselect_b32 s27, s7, s24
	s_cselect_b32 s24, s20, s50
	s_cselect_b32 s25, s21, s51
	s_add_u32 s22, s26, 0x4000
	s_addc_u32 s23, s27, 0
	s_add_i32 m0, s33, 0xc000
	v_lshl_add_u64 v[186:187], s[4:5], 0, v[158:159]
	global_load_lds_dwordx4 v[186:187], off
	s_add_i32 m0, s33, 0xe000
	v_lshl_add_u64 v[186:187], s[4:5], 0, v[160:161]
	global_load_lds_dwordx4 v[186:187], off
	s_mov_b32 s55, 0x10000
	v_add_u32_e32 v140, s55, v207
	ds_read_b128 v[128:131], v140
	ds_read_b128 v[136:139], v140 offset:2048
	ds_read_b128 v[132:135], v140 offset:1024
	ds_read_b128 v[140:143], v140 offset:3072
	ds_read_b128 v[144:147], v209
	ds_read_b128 v[162:165], v209 offset:2048
	ds_read_b128 v[170:173], v209 offset:4096
	ds_read_b128 v[178:181], v209 offset:6144
	ds_read_b128 v[148:151], v209 offset:1024
	ds_read_b128 v[166:169], v209 offset:3072
	ds_read_b128 v[174:177], v209 offset:5120
	ds_read_b128 v[182:185], v209 offset:7168
	s_mov_b32 s58, 0x14000
	s_add_i32 s55, s55, s31
	v_add_u32_e32 v198, s58, v207
	ds_read_b128 v[186:189], v198
	ds_read_b128 v[194:197], v198 offset:2048
	ds_read_b128 v[190:193], v198 offset:1024
	ds_read_b128 v[198:201], v198 offset:3072
	s_waitcnt lgkmcnt(0)
	s_barrier
; #define PG8_STAGE(bufoff, gbase, voff) do { _Pragma("unroll") for (int _i = 0; _i < 2; ++_i) \
;         __builtin_amdgcn_global_load_lds((const unsigned*)((const char*)(gbase) + (voff)[_i]), (LAS unsigned*)(lds + (bufoff) + ldsw + _i * 8192), 16, 0, 0); } while (0)
; #define PG8_LDA(dst, b, h) do { _Pragma("unroll") for (int m = 0; m < 4; ++m) _Pragma("unroll") for (int k = 0; k < 2; ++k) dst[m][k] = *(const LAS bf16x8*)(lds + PG8_SA(b, h) + aoff + m * 2048 + k * 1024); } while (0)
; #define PG8_LDB(dst, b, h) do { _Pragma("unroll") for (int n = 0; n < 2; ++n) _Pragma("unroll") for (int k = 0; k < 2; ++k) dst[n][k] = *(const LAS bf16x8*)(lds + PG8_SB(b, h) + boff + n * 2048 + k * 1024); } while (0)
; #define PG8_MMA(ai, bj, At, Bt) do { __builtin_amdgcn_s_setprio(1); _Pragma("unroll") for (int m = 0; m < 4; ++m) _Pragma("unroll") for (int n = 0; n < 2; ++n) _Pragma("unroll") for (int k = 0; k < 2; ++k) \
;         acc[ai][bj][m][n] = __builtin_amdgcn_mfma_f32_16x16x32_bf16(Bt[n][k], At[m][k], acc[ai][bj][m][n], 0, 0, 0); __builtin_amdgcn_s_setprio(0); } while (0)
; #define PG8_WAIT_V(n) asm volatile("s_waitcnt vmcnt(" #n ")" ::: "memory")
; #define PG8_WAIT_L(n) asm volatile("s_waitcnt lgkmcnt(" #n ")" ::: "memory")
; #define PG8_BAR __builtin_amdgcn_s_barrier()
; #define PG8_SCHED __builtin_amdgcn_sched_barrier(0)
; template <class Epi>
; __device__ __forceinline__ void gemm_phase(LAS unsigned char* lds, const Gemm g, const StaticOrder& S, const Epi& E) {
;     ...
;             PG8_WAIT_L(8); PG8_BAR; PG8_WAIT_L(0); PG8_MMA(0, 0, At, B0); PG8_BAR; PG8_SCHED;
;             PG8_LDB(B1, 0, 1); PG8_STAGE(PG8_SB(0, 0), b2, voffB);
;             PG8_BAR; PG8_WAIT_L(0); PG8_MMA(0, 1, At, B1); PG8_BAR;
;             PG8_LDA(At, 0, 1); PG8_STAGE(PG8_SA(0, 0), a2, voffA);
;             PG8_BAR; PG8_WAIT_L(0); PG8_MMA(1, 0, At, B0); PG8_BAR; PG8_SCHED;
;             PG8_STAGE(PG8_SB(0, 1), b2 + hstepB, voffB);
;             PG8_WAIT_V(6); PG8_BAR; PG8_MMA(1, 1, At, B1); PG8_BAR;
;             PG8_LDB(B0, 1, 0); PG8_SCHED; PG8_LDA(At, 1, 0); PG8_STAGE(PG8_SA(0, 1), a2 + hstepA, voffA);
;             PG8_WAIT_L(8); PG8_BAR; PG8_WAIT_L(0); PG8_MMA(0, 0, At, B0); PG8_BAR; PG8_SCHED;
	v_mfma_f32_16x16x32_bf16 v[124:127], v[128:131], v[144:147], v[124:127]
	v_mfma_f32_16x16x32_bf16 v[120:123], v[136:139], v[144:147], v[120:123]
	v_mfma_f32_16x16x32_bf16 v[116:119], v[128:131], v[162:165], v[116:119]
	v_mfma_f32_16x16x32_bf16 v[112:115], v[136:139], v[162:165], v[112:115]
	v_mfma_f32_16x16x32_bf16 v[108:111], v[128:131], v[170:173], v[108:111]
	v_mfma_f32_16x16x32_bf16 v[104:107], v[136:139], v[170:173], v[104:107]
	v_mfma_f32_16x16x32_bf16 v[100:103], v[128:131], v[178:181], v[100:103]
	v_mfma_f32_16x16x32_bf16 v[96:99], v[136:139], v[178:181], v[96:99]
	v_mfma_f32_16x16x32_bf16 v[124:127], v[132:135], v[148:151], v[124:127]
	v_mfma_f32_16x16x32_bf16 v[120:123], v[140:143], v[148:151], v[120:123]
	v_mfma_f32_16x16x32_bf16 v[116:119], v[132:135], v[166:169], v[116:119]
	v_mfma_f32_16x16x32_bf16 v[112:115], v[140:143], v[166:169], v[112:115]
	v_mfma_f32_16x16x32_bf16 v[108:111], v[132:135], v[174:177], v[108:111]
	v_mfma_f32_16x16x32_bf16 v[104:107], v[140:143], v[174:177], v[104:107]
	v_mfma_f32_16x16x32_bf16 v[100:103], v[132:135], v[182:185], v[100:103]
	v_mfma_f32_16x16x32_bf16 v[96:99], v[140:143], v[182:185], v[96:99]
	v_mfma_f32_16x16x32_bf16 v[92:95], v[186:189], v[144:147], v[92:95]
	v_mfma_f32_16x16x32_bf16 v[88:91], v[194:197], v[144:147], v[88:91]
	v_mfma_f32_16x16x32_bf16 v[84:87], v[186:189], v[162:165], v[84:87]
	v_mfma_f32_16x16x32_bf16 v[80:83], v[194:197], v[162:165], v[80:83]
	v_mfma_f32_16x16x32_bf16 v[76:79], v[186:189], v[170:173], v[76:79]
	v_mfma_f32_16x16x32_bf16 v[72:75], v[194:197], v[170:173], v[72:75]
	v_mfma_f32_16x16x32_bf16 v[68:71], v[186:189], v[178:181], v[68:71]
	v_mfma_f32_16x16x32_bf16 v[64:67], v[194:197], v[178:181], v[64:67]
	v_mfma_f32_16x16x32_bf16 v[92:95], v[190:193], v[148:151], v[92:95]
	v_mfma_f32_16x16x32_bf16 v[88:91], v[198:201], v[148:151], v[88:91]
	v_mfma_f32_16x16x32_bf16 v[84:87], v[190:193], v[166:169], v[84:87]
	v_mfma_f32_16x16x32_bf16 v[80:83], v[198:201], v[166:169], v[80:83]
	v_mfma_f32_16x16x32_bf16 v[76:79], v[190:193], v[174:177], v[76:79]
	v_mfma_f32_16x16x32_bf16 v[72:75], v[198:201], v[174:177], v[72:75]
	v_mfma_f32_16x16x32_bf16 v[68:71], v[190:193], v[182:185], v[68:71]
	v_mfma_f32_16x16x32_bf16 v[64:67], v[198:201], v[182:185], v[64:67]
	s_barrier
	s_mov_b32 m0, s55
	v_lshl_add_u64 v[202:203], s[24:25], 0, v[152:153]
	global_load_lds_dwordx4 v[202:203], off
	s_add_i32 m0, s55, 0x2000
	v_lshl_add_u64 v[202:203], s[24:25], 0, v[156:157]
	global_load_lds_dwordx4 v[202:203], off
	s_mov_b32 m0, s33
	v_lshl_add_u64 v[202:203], s[26:27], 0, v[152:153]
	global_load_lds_dwordx4 v[202:203], off
	s_mov_b32 m0, s34
	v_lshl_add_u64 v[202:203], s[26:27], 0, v[156:157]
	global_load_lds_dwordx4 v[202:203], off
	s_add_u32 s56, s24, s52
	s_addc_u32 s57, s25, 0
	s_add_i32 s55, s58, s31
	s_mov_b32 m0, s55
	v_lshl_add_u64 v[202:203], s[56:57], 0, v[152:153]
	global_load_lds_dwordx4 v[202:203], off
	s_add_i32 m0, s55, 0x2000
	v_lshl_add_u64 v[202:203], s[56:57], 0, v[156:157]
	global_load_lds_dwordx4 v[202:203], off
	ds_read_b128 v[144:147], v209 offset:16384
	ds_read_b128 v[162:165], v209 offset:18432
	ds_read_b128 v[170:173], v209 offset:20480
	ds_read_b128 v[178:181], v209 offset:22528
	ds_read_b128 v[148:151], v209 offset:17408
	ds_read_b128 v[166:169], v209 offset:19456
	ds_read_b128 v[174:177], v209 offset:21504
	ds_read_b128 v[182:185], v209 offset:23552
	s_waitcnt vmcnt(6)
	s_waitcnt lgkmcnt(0)
	s_barrier
	v_mfma_f32_16x16x32_bf16 v[60:63], v[128:131], v[144:147], v[60:63]
	v_mfma_f32_16x16x32_bf16 v[56:59], v[136:139], v[144:147], v[56:59]
	v_mfma_f32_16x16x32_bf16 v[52:55], v[128:131], v[162:165], v[52:55]
	v_mfma_f32_16x16x32_bf16 v[48:51], v[136:139], v[162:165], v[48:51]
	v_mfma_f32_16x16x32_bf16 v[44:47], v[128:131], v[170:173], v[44:47]
	v_mfma_f32_16x16x32_bf16 v[40:43], v[136:139], v[170:173], v[40:43]
	v_mfma_f32_16x16x32_bf16 v[36:39], v[128:131], v[178:181], v[36:39]
	v_mfma_f32_16x16x32_bf16 v[32:35], v[136:139], v[178:181], v[32:35]
	v_mfma_f32_16x16x32_bf16 v[60:63], v[132:135], v[148:151], v[60:63]
	v_mfma_f32_16x16x32_bf16 v[56:59], v[140:143], v[148:151], v[56:59]
	v_mfma_f32_16x16x32_bf16 v[52:55], v[132:135], v[166:169], v[52:55]
	v_mfma_f32_16x16x32_bf16 v[48:51], v[140:143], v[166:169], v[48:51]
	v_mfma_f32_16x16x32_bf16 v[44:47], v[132:135], v[174:177], v[44:47]
	v_mfma_f32_16x16x32_bf16 v[40:43], v[140:143], v[174:177], v[40:43]
	v_mfma_f32_16x16x32_bf16 v[36:39], v[132:135], v[182:185], v[36:39]
	v_mfma_f32_16x16x32_bf16 v[32:35], v[140:143], v[182:185], v[32:35]
	v_mfma_f32_16x16x32_bf16 v[28:31], v[186:189], v[144:147], v[28:31]
	v_mfma_f32_16x16x32_bf16 v[24:27], v[194:197], v[144:147], v[24:27]
	s_add_i32 s55, 0, 0x18000
	v_add_u32_e32 v140, s55, v207
	v_mfma_f32_16x16x32_bf16 v[20:23], v[186:189], v[162:165], v[20:23]
	v_mfma_f32_16x16x32_bf16 v[16:19], v[194:197], v[162:165], v[16:19]
	v_mfma_f32_16x16x32_bf16 v[12:15], v[186:189], v[170:173], v[12:15]
	v_mfma_f32_16x16x32_bf16 v[8:11], v[194:197], v[170:173], v[8:11]
	v_mfma_f32_16x16x32_bf16 v[4:7], v[186:189], v[178:181], v[4:7]
	v_mfma_f32_16x16x32_bf16 v[0:3], v[194:197], v[178:181], v[0:3]
	v_mfma_f32_16x16x32_bf16 v[28:31], v[190:193], v[148:151], v[28:31]
	v_mfma_f32_16x16x32_bf16 v[24:27], v[198:201], v[148:151], v[24:27]
	v_mfma_f32_16x16x32_bf16 v[20:23], v[190:193], v[166:169], v[20:23]
	v_mfma_f32_16x16x32_bf16 v[16:19], v[198:201], v[166:169], v[16:19]
	v_mfma_f32_16x16x32_bf16 v[12:15], v[190:193], v[174:177], v[12:15]
	v_mfma_f32_16x16x32_bf16 v[8:11], v[198:201], v[174:177], v[8:11]
	v_mfma_f32_16x16x32_bf16 v[4:7], v[190:193], v[182:185], v[4:7]
	v_mfma_f32_16x16x32_bf16 v[0:3], v[198:201], v[182:185], v[0:3]
	s_barrier
; #define PG8_STAGE(bufoff, gbase, voff) do { _Pragma("unroll") for (int _i = 0; _i < 2; ++_i) \
;         __builtin_amdgcn_global_load_lds((const unsigned*)((const char*)(gbase) + (voff)[_i]), (LAS unsigned*)(lds + (bufoff) + ldsw + _i * 8192), 16, 0, 0); } while (0)
; #define PG8_LDA(dst, b, h) do { _Pragma("unroll") for (int m = 0; m < 4; ++m) _Pragma("unroll") for (int k = 0; k < 2; ++k) dst[m][k] = *(const LAS bf16x8*)(lds + PG8_SA(b, h) + aoff + m * 2048 + k * 1024); } while (0)
; #define PG8_LDB(dst, b, h) do { _Pragma("unroll") for (int n = 0; n < 2; ++n) _Pragma("unroll") for (int k = 0; k < 2; ++k) dst[n][k] = *(const LAS bf16x8*)(lds + PG8_SB(b, h) + boff + n * 2048 + k * 1024); } while (0)
; #define PG8_MMA(ai, bj, At, Bt) do { __builtin_amdgcn_s_setprio(1); _Pragma("unroll") for (int m = 0; m < 4; ++m) _Pragma("unroll") for (int n = 0; n < 2; ++n) _Pragma("unroll") for (int k = 0; k < 2; ++k) \
;         acc[ai][bj][m][n] = __builtin_amdgcn_mfma_f32_16x16x32_bf16(Bt[n][k], At[m][k], acc[ai][bj][m][n], 0, 0, 0); __builtin_amdgcn_s_setprio(0); } while (0)
; #define PG8_WAIT_V(n) asm volatile("s_waitcnt vmcnt(" #n ")" ::: "memory")
; #define PG8_WAIT_L(n) asm volatile("s_waitcnt lgkmcnt(" #n ")" ::: "memory")
; #define PG8_BAR __builtin_amdgcn_s_barrier()
; #define PG8_SCHED __builtin_amdgcn_sched_barrier(0)
; template <class Epi>
; __device__ __forceinline__ void gemm_phase(LAS unsigned char* lds, const Gemm g, const StaticOrder& S, const Epi& E) {
;     ...
;             PG8_LDB(B1, 1, 1); PG8_STAGE(PG8_SB(1, 0), b3, voffB);
;             PG8_BAR; PG8_WAIT_L(0); PG8_MMA(0, 1, At, B1); PG8_BAR;
;             PG8_LDA(At, 1, 1); PG8_STAGE(PG8_SA(1, 0), a3, voffA);
;             PG8_BAR; PG8_WAIT_L(0); PG8_MMA(1, 0, At, B0); PG8_BAR; PG8_SCHED;
;             PG8_STAGE(PG8_SB(1, 1), b3 + hstepB, voffB);
;             PG8_WAIT_V(6); PG8_BAR; PG8_MMA(1, 1, At, B1); PG8_BAR;
	s_add_u32 s26, s26, s52
	s_addc_u32 s27, s27, 0
	s_mov_b32 m0, s35
	v_lshl_add_u64 v[186:187], s[26:27], 0, v[152:153]
	global_load_lds_dwordx4 v[186:187], off
	s_mov_b32 m0, s36
	v_lshl_add_u64 v[186:187], s[26:27], 0, v[156:157]
	global_load_lds_dwordx4 v[186:187], off
	ds_read_b128 v[128:131], v140
	ds_read_b128 v[136:139], v140 offset:2048
	ds_read_b128 v[132:135], v140 offset:1024
	ds_read_b128 v[140:143], v140 offset:3072
	ds_read_b128 v[144:147], v209 offset:32768
	ds_read_b128 v[162:165], v209 offset:34816
	ds_read_b128 v[170:173], v209 offset:36864
	ds_read_b128 v[178:181], v209 offset:38912
	ds_read_b128 v[148:151], v209 offset:33792
	ds_read_b128 v[166:169], v209 offset:35840
	ds_read_b128 v[174:177], v209 offset:37888
	ds_read_b128 v[182:185], v209 offset:39936
	s_mov_b32 s26, 0x1c000
	s_add_u32 s24, s24, 0x4000
	s_addc_u32 s25, s25, 0
	s_add_i32 s27, s55, s31
	v_add_u32_e32 v198, s26, v207
	ds_read_b128 v[186:189], v198
	ds_read_b128 v[194:197], v198 offset:2048
	ds_read_b128 v[190:193], v198 offset:1024
	ds_read_b128 v[198:201], v198 offset:3072
	s_waitcnt lgkmcnt(0)
	s_barrier
	v_mfma_f32_16x16x32_bf16 v[124:127], v[128:131], v[144:147], v[124:127]
	v_mfma_f32_16x16x32_bf16 v[120:123], v[136:139], v[144:147], v[120:123]
	v_mfma_f32_16x16x32_bf16 v[116:119], v[128:131], v[162:165], v[116:119]
	v_mfma_f32_16x16x32_bf16 v[112:115], v[136:139], v[162:165], v[112:115]
	v_mfma_f32_16x16x32_bf16 v[108:111], v[128:131], v[170:173], v[108:111]
	v_mfma_f32_16x16x32_bf16 v[104:107], v[136:139], v[170:173], v[104:107]
	v_mfma_f32_16x16x32_bf16 v[100:103], v[128:131], v[178:181], v[100:103]
	v_mfma_f32_16x16x32_bf16 v[96:99], v[136:139], v[178:181], v[96:99]
	v_mfma_f32_16x16x32_bf16 v[124:127], v[132:135], v[148:151], v[124:127]
	v_mfma_f32_16x16x32_bf16 v[120:123], v[140:143], v[148:151], v[120:123]
	v_mfma_f32_16x16x32_bf16 v[116:119], v[132:135], v[166:169], v[116:119]
	v_mfma_f32_16x16x32_bf16 v[112:115], v[140:143], v[166:169], v[112:115]
	v_mfma_f32_16x16x32_bf16 v[108:111], v[132:135], v[174:177], v[108:111]
	v_mfma_f32_16x16x32_bf16 v[104:107], v[140:143], v[174:177], v[104:107]
	v_mfma_f32_16x16x32_bf16 v[100:103], v[132:135], v[182:185], v[100:103]
	v_mfma_f32_16x16x32_bf16 v[96:99], v[140:143], v[182:185], v[96:99]
	v_mfma_f32_16x16x32_bf16 v[92:95], v[186:189], v[144:147], v[92:95]
	v_mfma_f32_16x16x32_bf16 v[88:91], v[194:197], v[144:147], v[88:91]
	v_mfma_f32_16x16x32_bf16 v[84:87], v[186:189], v[162:165], v[84:87]
	v_mfma_f32_16x16x32_bf16 v[80:83], v[194:197], v[162:165], v[80:83]
	v_mfma_f32_16x16x32_bf16 v[76:79], v[186:189], v[170:173], v[76:79]
	v_mfma_f32_16x16x32_bf16 v[72:75], v[194:197], v[170:173], v[72:75]
	v_mfma_f32_16x16x32_bf16 v[68:71], v[186:189], v[178:181], v[68:71]
	v_mfma_f32_16x16x32_bf16 v[64:67], v[194:197], v[178:181], v[64:67]
	v_mfma_f32_16x16x32_bf16 v[92:95], v[190:193], v[148:151], v[92:95]
	v_mfma_f32_16x16x32_bf16 v[88:91], v[198:201], v[148:151], v[88:91]
	v_mfma_f32_16x16x32_bf16 v[84:87], v[190:193], v[166:169], v[84:87]
	v_mfma_f32_16x16x32_bf16 v[80:83], v[198:201], v[166:169], v[80:83]
	v_mfma_f32_16x16x32_bf16 v[76:79], v[190:193], v[174:177], v[76:79]
	v_mfma_f32_16x16x32_bf16 v[72:75], v[198:201], v[174:177], v[72:75]
	v_mfma_f32_16x16x32_bf16 v[68:71], v[190:193], v[182:185], v[68:71]
	v_mfma_f32_16x16x32_bf16 v[64:67], v[198:201], v[182:185], v[64:67]
	s_barrier
	s_mov_b32 m0, s27
	v_lshl_add_u64 v[202:203], s[24:25], 0, v[152:153]
	global_load_lds_dwordx4 v[202:203], off
	s_add_i32 m0, s27, 0x2000
	v_lshl_add_u64 v[202:203], s[24:25], 0, v[156:157]
	global_load_lds_dwordx4 v[202:203], off
	s_mov_b32 m0, s38
	v_lshl_add_u64 v[202:203], s[22:23], 0, v[152:153]
	global_load_lds_dwordx4 v[202:203], off
	s_mov_b32 m0, s39
	v_lshl_add_u64 v[202:203], s[22:23], 0, v[156:157]
	global_load_lds_dwordx4 v[202:203], off
	s_add_u32 s22, s24, s52
	s_addc_u32 s23, s25, 0
	s_add_i32 s24, s26, s31
	s_mov_b32 m0, s24
	v_lshl_add_u64 v[202:203], s[22:23], 0, v[152:153]
	global_load_lds_dwordx4 v[202:203], off
	s_add_i32 m0, s24, 0x2000
	v_lshl_add_u64 v[202:203], s[22:23], 0, v[156:157]
	global_load_lds_dwordx4 v[202:203], off
	ds_read_b128 v[144:147], v209 offset:49152
	ds_read_b128 v[162:165], v209 offset:51200
	ds_read_b128 v[170:173], v209 offset:53248
	ds_read_b128 v[178:181], v209 offset:55296
	ds_read_b128 v[148:151], v209 offset:50176
	ds_read_b128 v[166:169], v209 offset:52224
	ds_read_b128 v[174:177], v209 offset:54272
	ds_read_b128 v[182:185], v209 offset:56320
	s_waitcnt vmcnt(6)
	s_waitcnt lgkmcnt(0)
	s_barrier
	v_mfma_f32_16x16x32_bf16 v[60:63], v[128:131], v[144:147], v[60:63]
	v_mfma_f32_16x16x32_bf16 v[56:59], v[136:139], v[144:147], v[56:59]
	v_mfma_f32_16x16x32_bf16 v[52:55], v[128:131], v[162:165], v[52:55]
	v_mfma_f32_16x16x32_bf16 v[48:51], v[136:139], v[162:165], v[48:51]
	v_mfma_f32_16x16x32_bf16 v[44:47], v[128:131], v[170:173], v[44:47]
	v_mfma_f32_16x16x32_bf16 v[40:43], v[136:139], v[170:173], v[40:43]
	v_mfma_f32_16x16x32_bf16 v[36:39], v[128:131], v[178:181], v[36:39]
	v_mfma_f32_16x16x32_bf16 v[32:35], v[136:139], v[178:181], v[32:35]
	v_mfma_f32_16x16x32_bf16 v[60:63], v[132:135], v[148:151], v[60:63]
	v_mfma_f32_16x16x32_bf16 v[56:59], v[140:143], v[148:151], v[56:59]
	v_mfma_f32_16x16x32_bf16 v[52:55], v[132:135], v[166:169], v[52:55]
	v_mfma_f32_16x16x32_bf16 v[48:51], v[140:143], v[166:169], v[48:51]
	v_mfma_f32_16x16x32_bf16 v[44:47], v[132:135], v[174:177], v[44:47]
	v_mfma_f32_16x16x32_bf16 v[40:43], v[140:143], v[174:177], v[40:43]
	v_mfma_f32_16x16x32_bf16 v[36:39], v[132:135], v[182:185], v[36:39]
	v_mfma_f32_16x16x32_bf16 v[32:35], v[140:143], v[182:185], v[32:35]
	v_mfma_f32_16x16x32_bf16 v[28:31], v[186:189], v[144:147], v[28:31]
	v_mfma_f32_16x16x32_bf16 v[24:27], v[194:197], v[144:147], v[24:27]
	s_add_u32 s4, s4, 0x8000
	s_addc_u32 s5, s5, 0
	s_add_u32 s50, s50, 0x8000
	s_addc_u32 s51, s51, 0
	v_mfma_f32_16x16x32_bf16 v[20:23], v[186:189], v[162:165], v[20:23]
	v_mfma_f32_16x16x32_bf16 v[16:19], v[194:197], v[162:165], v[16:19]
	v_mfma_f32_16x16x32_bf16 v[12:15], v[186:189], v[170:173], v[12:15]
	v_mfma_f32_16x16x32_bf16 v[8:11], v[194:197], v[170:173], v[8:11]
	v_mfma_f32_16x16x32_bf16 v[4:7], v[186:189], v[178:181], v[4:7]
	v_mfma_f32_16x16x32_bf16 v[0:3], v[194:197], v[178:181], v[0:3]
	v_mfma_f32_16x16x32_bf16 v[28:31], v[190:193], v[148:151], v[28:31]
	v_mfma_f32_16x16x32_bf16 v[24:27], v[198:201], v[148:151], v[24:27]
	v_mfma_f32_16x16x32_bf16 v[20:23], v[190:193], v[166:169], v[20:23]
	v_mfma_f32_16x16x32_bf16 v[16:19], v[198:201], v[166:169], v[16:19]
	v_mfma_f32_16x16x32_bf16 v[12:15], v[190:193], v[174:177], v[12:15]
	v_mfma_f32_16x16x32_bf16 v[8:11], v[198:201], v[174:177], v[8:11]
	v_mfma_f32_16x16x32_bf16 v[4:7], v[190:193], v[182:185], v[4:7]
	s_cmp_ge_u32 s54, s28
	s_mov_b32 s22, s54
	v_mfma_f32_16x16x32_bf16 v[0:3], v[198:201], v[182:185], v[0:3]
	s_barrier
	s_cbranch_scc0 .LBB0_187

; #define PG8_STAGE(bufoff, gbase, voff) do { _Pragma("unroll") for (int _i = 0; _i < 2; ++_i) \
;         __builtin_amdgcn_global_load_lds((const unsigned*)((const char*)(gbase) + (voff)[_i]), (LAS unsigned*)(lds + (bufoff) + ldsw + _i * 8192), 16, 0, 0); } while (0)
; #define PG8_LDA(dst, b, h) do { _Pragma("unroll") for (int m = 0; m < 4; ++m) _Pragma("unroll") for (int k = 0; k < 2; ++k) dst[m][k] = *(const LAS bf16x8*)(lds + PG8_SA(b, h) + aoff + m * 2048 + k * 1024); } while (0)
; #define PG8_LDB(dst, b, h) do { _Pragma("unroll") for (int n = 0; n < 2; ++n) _Pragma("unroll") for (int k = 0; k < 2; ++k) dst[n][k] = *(const LAS bf16x8*)(lds + PG8_SB(b, h) + boff + n * 2048 + k * 1024); } while (0)
; #define PG8_WAIT_V(n) asm volatile("s_waitcnt vmcnt(" #n ")" ::: "memory")
; #define PG8_WAIT_L(n) asm volatile("s_waitcnt lgkmcnt(" #n ")" ::: "memory")
; #define PG8_BAR __builtin_amdgcn_s_barrier()
; #define PG8_SCHED __builtin_amdgcn_sched_barrier(0)
; template <class Epi>
; __device__ __forceinline__ void gemm_phase(LAS unsigned char* lds, const Gemm g, const StaticOrder& S, const Epi& E) {
;     ...
;         const bool has_next = S.next(ui + 1, nxt);
;         const char* nA = has_next ? (const char*)g.A + (size_t)nxt.pm * tstepA : cA; const char* nB = has_next ? (const char*)g.Bt + (size_t)nxt.pn * tstepB : cB;
;         for (int t = 0; t < nt; t += 2) {
;             const bool last = (t == nt - 2);
;             const char* a1 = cA + (size_t)(t + 1) * kstep;
;             const char* a2 = last ? nA : cA + (size_t)(t + 2) * kstep; const char* b2 = last ? nB : cB + (size_t)(t + 2) * kstep;
;             const char* a3 = a2 + kstep; const char* b3 = b2 + kstep;
;             PG8_LDB(B0, 0, 0); PG8_SCHED; PG8_LDA(At, 0, 0); PG8_STAGE(PG8_SA(1, 1), a1 + hstepA, voffA);
;             PG8_WAIT_L(8); PG8_BAR; PG8_WAIT_L(0); PG8_MMA(0, 0, At, B0); PG8_BAR; PG8_SCHED;
;             PG8_LDB(B1, 0, 1); PG8_STAGE(PG8_SB(0, 0), b2, voffB);
;             PG8_BAR; PG8_WAIT_L(0); PG8_MMA(0, 1, At, B1); PG8_BAR;
;             PG8_LDA(At, 0, 1); PG8_STAGE(PG8_SA(0, 0), a2, voffA);
;             PG8_BAR; PG8_WAIT_L(0); PG8_MMA(1, 0, At, B0); PG8_BAR; PG8_SCHED;
;             PG8_STAGE(PG8_SB(0, 1), b2 + hstepB, voffB);
;             PG8_WAIT_V(6); PG8_BAR; PG8_MMA(1, 1, At, B1); PG8_BAR;
.LBB0_246:
	s_ashr_i32 s5, s4, 31
	v_cmp_lt_i64_e32 vcc, s[6:7], v[154:155]
	s_lshl_b64 s[6:7], s[4:5], 20
	v_readlane_b32 s8, v252, 53
	v_readlane_b32 s9, v252, 54
	s_add_u32 s6, s8, s6
	s_addc_u32 s7, s9, s7
	s_and_b64 s[8:9], vcc, exec
	s_cselect_b32 s5, s7, s13
	s_cselect_b32 s11, s6, s12
	s_ashr_i32 s3, s2, 31
	s_lshl_b64 s[8:9], s[2:3], 20
	s_add_u32 s8, s21, s8
	s_addc_u32 s9, s22, s9
	s_and_b64 s[16:17], vcc, exec
	s_cselect_b32 s3, s9, s15
	s_cselect_b32 s35, s8, s14
	s_add_u32 s12, s12, 0x84000
	s_addc_u32 s13, s13, 0
	s_add_u32 s36, s14, 0x8000
	s_addc_u32 s37, s15, 0
	s_mov_b32 s38, -2
	s_add_u32 s14, s12, 0xfff84000
	s_addc_u32 s15, s13, -1
	s_cmp_eq_u32 s38, 28
	s_cselect_b32 s18, s11, s14
	s_cselect_b32 s19, s5, s15
	s_cselect_b32 s14, s35, s36
	s_cselect_b32 s15, s3, s37
	s_add_u32 s16, s18, 0x4000
	s_addc_u32 s17, s19, 0
	s_add_i32 m0, s25, 0xc000
	v_lshl_add_u64 v[194:195], s[12:13], 0, v[156:157]
	global_load_lds_dwordx4 v[194:195], off
	s_add_i32 m0, s25, 0xe000
	v_lshl_add_u64 v[194:195], s[12:13], 0, v[158:159]
	global_load_lds_dwordx4 v[194:195], off
	s_mov_b32 s39, 0x10000
	v_add_u32_e32 v140, s39, v170
	ds_read_b128 v[128:131], v140
	ds_read_b128 v[136:139], v140 offset:2048
	ds_read_b128 v[132:135], v140 offset:1024
	ds_read_b128 v[140:143], v140 offset:3072
	ds_read_b128 v[144:147], v172
	ds_read_b128 v[166:169], v172 offset:2048
	ds_read_b128 v[178:181], v172 offset:4096
	ds_read_b128 v[186:189], v172 offset:6144
	ds_read_b128 v[148:151], v172 offset:1024
	ds_read_b128 v[174:177], v172 offset:3072
	ds_read_b128 v[182:185], v172 offset:5120
	ds_read_b128 v[190:193], v172 offset:7168
	s_mov_b32 s42, 0x14000
	s_add_i32 s39, s39, s23
	v_add_u32_e32 v152, s42, v170
	ds_read_b128 v[194:197], v152
	ds_read_b128 v[202:205], v152 offset:2048
	ds_read_b128 v[198:201], v152 offset:1024
	ds_read_b128 v[206:209], v152 offset:3072
	s_waitcnt lgkmcnt(0)
	s_barrier
	v_mfma_f32_16x16x32_bf16 v[124:127], v[128:131], v[144:147], 0
	v_mfma_f32_16x16x32_bf16 v[120:123], v[136:139], v[144:147], 0
	v_mfma_f32_16x16x32_bf16 v[108:111], v[128:131], v[166:169], 0
	v_mfma_f32_16x16x32_bf16 v[104:107], v[136:139], v[166:169], 0
	v_mfma_f32_16x16x32_bf16 v[92:95], v[128:131], v[178:181], 0
	v_mfma_f32_16x16x32_bf16 v[88:91], v[136:139], v[178:181], 0
	v_mfma_f32_16x16x32_bf16 v[76:79], v[128:131], v[186:189], 0
	v_mfma_f32_16x16x32_bf16 v[72:75], v[136:139], v[186:189], 0
	v_mfma_f32_16x16x32_bf16 v[124:127], v[132:135], v[148:151], v[124:127]
	v_mfma_f32_16x16x32_bf16 v[120:123], v[140:143], v[148:151], v[120:123]
	v_mfma_f32_16x16x32_bf16 v[108:111], v[132:135], v[174:177], v[108:111]
	v_mfma_f32_16x16x32_bf16 v[104:107], v[140:143], v[174:177], v[104:107]
	v_mfma_f32_16x16x32_bf16 v[92:95], v[132:135], v[182:185], v[92:95]
	v_mfma_f32_16x16x32_bf16 v[88:91], v[140:143], v[182:185], v[88:91]
	v_mfma_f32_16x16x32_bf16 v[76:79], v[132:135], v[190:193], v[76:79]
	v_mfma_f32_16x16x32_bf16 v[72:75], v[140:143], v[190:193], v[72:75]
	v_mfma_f32_16x16x32_bf16 v[116:119], v[194:197], v[144:147], 0
	v_mfma_f32_16x16x32_bf16 v[112:115], v[202:205], v[144:147], 0
	v_mfma_f32_16x16x32_bf16 v[100:103], v[194:197], v[166:169], 0
	v_mfma_f32_16x16x32_bf16 v[96:99], v[202:205], v[166:169], 0
	v_mfma_f32_16x16x32_bf16 v[84:87], v[194:197], v[178:181], 0
	v_mfma_f32_16x16x32_bf16 v[80:83], v[202:205], v[178:181], 0
	v_mfma_f32_16x16x32_bf16 v[68:71], v[194:197], v[186:189], 0
	v_mfma_f32_16x16x32_bf16 v[64:67], v[202:205], v[186:189], 0
	v_mfma_f32_16x16x32_bf16 v[116:119], v[198:201], v[148:151], v[116:119]
	v_mfma_f32_16x16x32_bf16 v[112:115], v[206:209], v[148:151], v[112:115]
	v_mfma_f32_16x16x32_bf16 v[100:103], v[198:201], v[174:177], v[100:103]
	v_mfma_f32_16x16x32_bf16 v[96:99], v[206:209], v[174:177], v[96:99]
	v_mfma_f32_16x16x32_bf16 v[84:87], v[198:201], v[182:185], v[84:87]
	v_mfma_f32_16x16x32_bf16 v[80:83], v[206:209], v[182:185], v[80:83]
	v_mfma_f32_16x16x32_bf16 v[68:71], v[198:201], v[190:193], v[68:71]
	v_mfma_f32_16x16x32_bf16 v[64:67], v[206:209], v[190:193], v[64:67]
	s_barrier
	s_mov_b32 m0, s39
	v_lshl_add_u64 v[210:211], s[14:15], 0, v[156:157]
	global_load_lds_dwordx4 v[210:211], off
	s_add_i32 m0, s39, 0x2000
	v_lshl_add_u64 v[210:211], s[14:15], 0, v[158:159]
	global_load_lds_dwordx4 v[210:211], off
	s_mov_b32 m0, s25
	v_lshl_add_u64 v[210:211], s[18:19], 0, v[156:157]
	global_load_lds_dwordx4 v[210:211], off
	s_mov_b32 m0, s26
	v_lshl_add_u64 v[210:211], s[18:19], 0, v[158:159]
	global_load_lds_dwordx4 v[210:211], off
	s_add_u32 s40, s14, 0x80000
	s_addc_u32 s41, s15, 0
	s_add_i32 s39, s42, s23
	s_mov_b32 m0, s39
	v_lshl_add_u64 v[210:211], s[40:41], 0, v[156:157]
	global_load_lds_dwordx4 v[210:211], off
	s_add_i32 m0, s39, 0x2000
	v_lshl_add_u64 v[210:211], s[40:41], 0, v[158:159]
	global_load_lds_dwordx4 v[210:211], off
	ds_read_b128 v[144:147], v172 offset:16384
	ds_read_b128 v[166:169], v172 offset:18432
	ds_read_b128 v[178:181], v172 offset:20480
	ds_read_b128 v[186:189], v172 offset:22528
	ds_read_b128 v[148:151], v172 offset:17408
	ds_read_b128 v[174:177], v172 offset:19456
	ds_read_b128 v[182:185], v172 offset:21504
	ds_read_b128 v[190:193], v172 offset:23552
	s_waitcnt vmcnt(6)
	s_waitcnt lgkmcnt(0)
	s_barrier
; #define PG8_STAGE(bufoff, gbase, voff) do { _Pragma("unroll") for (int _i = 0; _i < 2; ++_i) \
;         __builtin_amdgcn_global_load_lds((const unsigned*)((const char*)(gbase) + (voff)[_i]), (LAS unsigned*)(lds + (bufoff) + ldsw + _i * 8192), 16, 0, 0); } while (0)
; #define PG8_LDA(dst, b, h) do { _Pragma("unroll") for (int m = 0; m < 4; ++m) _Pragma("unroll") for (int k = 0; k < 2; ++k) dst[m][k] = *(const LAS bf16x8*)(lds + PG8_SA(b, h) + aoff + m * 2048 + k * 1024); } while (0)
; #define PG8_LDB(dst, b, h) do { _Pragma("unroll") for (int n = 0; n < 2; ++n) _Pragma("unroll") for (int k = 0; k < 2; ++k) dst[n][k] = *(const LAS bf16x8*)(lds + PG8_SB(b, h) + boff + n * 2048 + k * 1024); } while (0)
; #define PG8_MMA(ai, bj, At, Bt) do { __builtin_amdgcn_s_setprio(1); _Pragma("unroll") for (int m = 0; m < 4; ++m) _Pragma("unroll") for (int n = 0; n < 2; ++n) _Pragma("unroll") for (int k = 0; k < 2; ++k) \
;         acc[ai][bj][m][n] = __builtin_amdgcn_mfma_f32_16x16x32_bf16(Bt[n][k], At[m][k], acc[ai][bj][m][n], 0, 0, 0); __builtin_amdgcn_s_setprio(0); } while (0)
; #define PG8_WAIT_V(n) asm volatile("s_waitcnt vmcnt(" #n ")" ::: "memory")
; #define PG8_WAIT_L(n) asm volatile("s_waitcnt lgkmcnt(" #n ")" ::: "memory")
; #define PG8_BAR __builtin_amdgcn_s_barrier()
; #define PG8_SCHED __builtin_amdgcn_sched_barrier(0)
; template <class Epi>
; __device__ __forceinline__ void gemm_phase(LAS unsigned char* lds, const Gemm g, const StaticOrder& S, const Epi& E) {
;     ...
;             PG8_BAR; PG8_WAIT_L(0); PG8_MMA(1, 0, At, B0); PG8_BAR; PG8_SCHED;
;             PG8_STAGE(PG8_SB(0, 1), b2 + hstepB, voffB);
;             PG8_WAIT_V(6); PG8_BAR; PG8_MMA(1, 1, At, B1); PG8_BAR;
;             PG8_LDB(B0, 1, 0); PG8_SCHED; PG8_LDA(At, 1, 0); PG8_STAGE(PG8_SA(0, 1), a2 + hstepA, voffA);
;             PG8_WAIT_L(8); PG8_BAR; PG8_WAIT_L(0); PG8_MMA(0, 0, At, B0); PG8_BAR; PG8_SCHED;
;             PG8_LDB(B1, 1, 1); PG8_STAGE(PG8_SB(1, 0), b3, voffB);
;             PG8_BAR; PG8_WAIT_L(0); PG8_MMA(0, 1, At, B1); PG8_BAR;
;             PG8_LDA(At, 1, 1); PG8_STAGE(PG8_SA(1, 0), a3, voffA);
;             PG8_BAR; PG8_WAIT_L(0); PG8_MMA(1, 0, At, B0); PG8_BAR; PG8_SCHED;
	v_mfma_f32_16x16x32_bf16 v[60:63], v[128:131], v[144:147], 0
	v_mfma_f32_16x16x32_bf16 v[56:59], v[136:139], v[144:147], 0
	v_mfma_f32_16x16x32_bf16 v[44:47], v[128:131], v[166:169], 0
	v_mfma_f32_16x16x32_bf16 v[40:43], v[136:139], v[166:169], 0
	v_mfma_f32_16x16x32_bf16 v[28:31], v[128:131], v[178:181], 0
	v_mfma_f32_16x16x32_bf16 v[24:27], v[136:139], v[178:181], 0
	v_mfma_f32_16x16x32_bf16 v[12:15], v[128:131], v[186:189], 0
	v_mfma_f32_16x16x32_bf16 v[8:11], v[136:139], v[186:189], 0
	v_mfma_f32_16x16x32_bf16 v[60:63], v[132:135], v[148:151], v[60:63]
	v_mfma_f32_16x16x32_bf16 v[56:59], v[140:143], v[148:151], v[56:59]
	v_mfma_f32_16x16x32_bf16 v[44:47], v[132:135], v[174:177], v[44:47]
	v_mfma_f32_16x16x32_bf16 v[40:43], v[140:143], v[174:177], v[40:43]
	v_mfma_f32_16x16x32_bf16 v[28:31], v[132:135], v[182:185], v[28:31]
	v_mfma_f32_16x16x32_bf16 v[24:27], v[140:143], v[182:185], v[24:27]
	v_mfma_f32_16x16x32_bf16 v[12:15], v[132:135], v[190:193], v[12:15]
	v_mfma_f32_16x16x32_bf16 v[8:11], v[140:143], v[190:193], v[8:11]
	v_mfma_f32_16x16x32_bf16 v[52:55], v[194:197], v[144:147], 0
	v_mfma_f32_16x16x32_bf16 v[48:51], v[202:205], v[144:147], 0
	s_add_i32 s39, 0, 0x18000
	v_add_u32_e32 v140, s39, v170
	v_mfma_f32_16x16x32_bf16 v[36:39], v[194:197], v[166:169], 0
	v_mfma_f32_16x16x32_bf16 v[32:35], v[202:205], v[166:169], 0
	v_mfma_f32_16x16x32_bf16 v[20:23], v[194:197], v[178:181], 0
	v_mfma_f32_16x16x32_bf16 v[16:19], v[202:205], v[178:181], 0
	v_mfma_f32_16x16x32_bf16 v[4:7], v[194:197], v[186:189], 0
	v_mfma_f32_16x16x32_bf16 v[0:3], v[202:205], v[186:189], 0
	v_mfma_f32_16x16x32_bf16 v[52:55], v[198:201], v[148:151], v[52:55]
	v_mfma_f32_16x16x32_bf16 v[48:51], v[206:209], v[148:151], v[48:51]
	v_mfma_f32_16x16x32_bf16 v[36:39], v[198:201], v[174:177], v[36:39]
	v_mfma_f32_16x16x32_bf16 v[32:35], v[206:209], v[174:177], v[32:35]
	v_mfma_f32_16x16x32_bf16 v[20:23], v[198:201], v[182:185], v[20:23]
	v_mfma_f32_16x16x32_bf16 v[16:19], v[206:209], v[182:185], v[16:19]
	v_mfma_f32_16x16x32_bf16 v[4:7], v[198:201], v[190:193], v[4:7]
	v_mfma_f32_16x16x32_bf16 v[0:3], v[206:209], v[190:193], v[0:3]
	s_barrier
	s_add_u32 s18, s18, 0x80000
	s_addc_u32 s19, s19, 0
	s_mov_b32 m0, s27
	v_lshl_add_u64 v[194:195], s[18:19], 0, v[156:157]
	global_load_lds_dwordx4 v[194:195], off
	s_mov_b32 m0, s28
	v_lshl_add_u64 v[194:195], s[18:19], 0, v[158:159]
	global_load_lds_dwordx4 v[194:195], off
	ds_read_b128 v[128:131], v140
	ds_read_b128 v[136:139], v140 offset:2048
	ds_read_b128 v[132:135], v140 offset:1024
	ds_read_b128 v[140:143], v140 offset:3072
	ds_read_b128 v[144:147], v172 offset:32768
	ds_read_b128 v[166:169], v172 offset:34816
	ds_read_b128 v[178:181], v172 offset:36864
	ds_read_b128 v[186:189], v172 offset:38912
	ds_read_b128 v[148:151], v172 offset:33792
	ds_read_b128 v[174:177], v172 offset:35840
	ds_read_b128 v[182:185], v172 offset:37888
	ds_read_b128 v[190:193], v172 offset:39936
	s_mov_b32 s40, 0x1c000
	s_add_u32 s18, s14, 0x4000
	s_addc_u32 s19, s15, 0
	s_add_i32 s39, s39, s23
	v_add_u32_e32 v152, s40, v170
	ds_read_b128 v[194:197], v152
	ds_read_b128 v[202:205], v152 offset:2048
	ds_read_b128 v[198:201], v152 offset:1024
	ds_read_b128 v[206:209], v152 offset:3072
	s_waitcnt lgkmcnt(0)
	s_barrier
	v_mfma_f32_16x16x32_bf16 v[124:127], v[128:131], v[144:147], v[124:127]
	v_mfma_f32_16x16x32_bf16 v[120:123], v[136:139], v[144:147], v[120:123]
	v_mfma_f32_16x16x32_bf16 v[108:111], v[128:131], v[166:169], v[108:111]
	v_mfma_f32_16x16x32_bf16 v[104:107], v[136:139], v[166:169], v[104:107]
	v_mfma_f32_16x16x32_bf16 v[92:95], v[128:131], v[178:181], v[92:95]
	v_mfma_f32_16x16x32_bf16 v[88:91], v[136:139], v[178:181], v[88:91]
	v_mfma_f32_16x16x32_bf16 v[76:79], v[128:131], v[186:189], v[76:79]
	v_mfma_f32_16x16x32_bf16 v[72:75], v[136:139], v[186:189], v[72:75]
	v_mfma_f32_16x16x32_bf16 v[124:127], v[132:135], v[148:151], v[124:127]
	v_mfma_f32_16x16x32_bf16 v[120:123], v[140:143], v[148:151], v[120:123]
	v_mfma_f32_16x16x32_bf16 v[108:111], v[132:135], v[174:177], v[108:111]
	v_mfma_f32_16x16x32_bf16 v[104:107], v[140:143], v[174:177], v[104:107]
	v_mfma_f32_16x16x32_bf16 v[92:95], v[132:135], v[182:185], v[92:95]
	v_mfma_f32_16x16x32_bf16 v[88:91], v[140:143], v[182:185], v[88:91]
	v_mfma_f32_16x16x32_bf16 v[76:79], v[132:135], v[190:193], v[76:79]
	v_mfma_f32_16x16x32_bf16 v[72:75], v[140:143], v[190:193], v[72:75]
	v_mfma_f32_16x16x32_bf16 v[116:119], v[194:197], v[144:147], v[116:119]
	v_mfma_f32_16x16x32_bf16 v[112:115], v[202:205], v[144:147], v[112:115]
	v_mfma_f32_16x16x32_bf16 v[100:103], v[194:197], v[166:169], v[100:103]
	v_mfma_f32_16x16x32_bf16 v[96:99], v[202:205], v[166:169], v[96:99]
	v_mfma_f32_16x16x32_bf16 v[84:87], v[194:197], v[178:181], v[84:87]
	v_mfma_f32_16x16x32_bf16 v[80:83], v[202:205], v[178:181], v[80:83]
	v_mfma_f32_16x16x32_bf16 v[68:71], v[194:197], v[186:189], v[68:71]
	v_mfma_f32_16x16x32_bf16 v[64:67], v[202:205], v[186:189], v[64:67]
	v_mfma_f32_16x16x32_bf16 v[116:119], v[198:201], v[148:151], v[116:119]
	v_mfma_f32_16x16x32_bf16 v[112:115], v[206:209], v[148:151], v[112:115]
	v_mfma_f32_16x16x32_bf16 v[100:103], v[198:201], v[174:177], v[100:103]
	v_mfma_f32_16x16x32_bf16 v[96:99], v[206:209], v[174:177], v[96:99]
	v_mfma_f32_16x16x32_bf16 v[84:87], v[198:201], v[182:185], v[84:87]
	v_mfma_f32_16x16x32_bf16 v[80:83], v[206:209], v[182:185], v[80:83]
	v_mfma_f32_16x16x32_bf16 v[68:71], v[198:201], v[190:193], v[68:71]
	v_mfma_f32_16x16x32_bf16 v[64:67], v[206:209], v[190:193], v[64:67]
	s_barrier
; #define PG8_STAGE(bufoff, gbase, voff) do { _Pragma("unroll") for (int _i = 0; _i < 2; ++_i) \
;         __builtin_amdgcn_global_load_lds((const unsigned*)((const char*)(gbase) + (voff)[_i]), (LAS unsigned*)(lds + (bufoff) + ldsw + _i * 8192), 16, 0, 0); } while (0)
; #define PG8_LDA(dst, b, h) do { _Pragma("unroll") for (int m = 0; m < 4; ++m) _Pragma("unroll") for (int k = 0; k < 2; ++k) dst[m][k] = *(const LAS bf16x8*)(lds + PG8_SA(b, h) + aoff + m * 2048 + k * 1024); } while (0)
; #define PG8_LDB(dst, b, h) do { _Pragma("unroll") for (int n = 0; n < 2; ++n) _Pragma("unroll") for (int k = 0; k < 2; ++k) dst[n][k] = *(const LAS bf16x8*)(lds + PG8_SB(b, h) + boff + n * 2048 + k * 1024); } while (0)
; #define PG8_MMA(ai, bj, At, Bt) do { __builtin_amdgcn_s_setprio(1); _Pragma("unroll") for (int m = 0; m < 4; ++m) _Pragma("unroll") for (int n = 0; n < 2; ++n) _Pragma("unroll") for (int k = 0; k < 2; ++k) \
;         acc[ai][bj][m][n] = __builtin_amdgcn_mfma_f32_16x16x32_bf16(Bt[n][k], At[m][k], acc[ai][bj][m][n], 0, 0, 0); __builtin_amdgcn_s_setprio(0); } while (0)
; #define PG8_WAIT_V(n) asm volatile("s_waitcnt vmcnt(" #n ")" ::: "memory")
; #define PG8_WAIT_L(n) asm volatile("s_waitcnt lgkmcnt(" #n ")" ::: "memory")
; #define PG8_BAR __builtin_amdgcn_s_barrier()
; #define PG8_SCHED __builtin_amdgcn_sched_barrier(0)
; template <class Epi>
; __device__ __forceinline__ void gemm_phase(LAS unsigned char* lds, const Gemm g, const StaticOrder& S, const Epi& E) {
;     ...
;         for (int t = 0; t < nt; t += 2) {
;             const bool last = (t == nt - 2);
;             const char* a1 = cA + (size_t)(t + 1) * kstep;
;             const char* a2 = last ? nA : cA + (size_t)(t + 2) * kstep; const char* b2 = last ? nB : cB + (size_t)(t + 2) * kstep;
;             const char* a3 = a2 + kstep; const char* b3 = b2 + kstep;
;             PG8_LDB(B0, 0, 0); PG8_SCHED; PG8_LDA(At, 0, 0); PG8_STAGE(PG8_SA(1, 1), a1 + hstepA, voffA);
;             PG8_WAIT_L(8); PG8_BAR; PG8_WAIT_L(0); PG8_MMA(0, 0, At, B0); PG8_BAR; PG8_SCHED;
;     ...
;             PG8_BAR; PG8_WAIT_L(0); PG8_MMA(0, 1, At, B1); PG8_BAR;
;             PG8_LDA(At, 1, 1); PG8_STAGE(PG8_SA(1, 0), a3, voffA);
;             PG8_BAR; PG8_WAIT_L(0); PG8_MMA(1, 0, At, B0); PG8_BAR; PG8_SCHED;
;             PG8_STAGE(PG8_SB(1, 1), b3 + hstepB, voffB);
;             PG8_WAIT_V(6); PG8_BAR; PG8_MMA(1, 1, At, B1); PG8_BAR;
	s_mov_b32 m0, s39
	v_lshl_add_u64 v[210:211], s[18:19], 0, v[156:157]
	global_load_lds_dwordx4 v[210:211], off
	s_add_i32 m0, s39, 0x2000
	v_lshl_add_u64 v[210:211], s[18:19], 0, v[158:159]
	global_load_lds_dwordx4 v[210:211], off
	s_mov_b32 m0, s29
	v_lshl_add_u64 v[210:211], s[16:17], 0, v[156:157]
	global_load_lds_dwordx4 v[210:211], off
	s_mov_b32 m0, s30
	v_lshl_add_u64 v[210:211], s[16:17], 0, v[158:159]
	global_load_lds_dwordx4 v[210:211], off
	s_add_u32 s14, s14, 0x84000
	s_addc_u32 s15, s15, 0
	s_add_i32 s16, s40, s23
	s_mov_b32 m0, s16
	v_lshl_add_u64 v[210:211], s[14:15], 0, v[156:157]
	global_load_lds_dwordx4 v[210:211], off
	s_add_i32 m0, s16, 0x2000
	v_lshl_add_u64 v[210:211], s[14:15], 0, v[158:159]
	global_load_lds_dwordx4 v[210:211], off
	ds_read_b128 v[144:147], v172 offset:49152
	ds_read_b128 v[166:169], v172 offset:51200
	ds_read_b128 v[178:181], v172 offset:53248
	ds_read_b128 v[186:189], v172 offset:55296
	ds_read_b128 v[148:151], v172 offset:50176
	ds_read_b128 v[174:177], v172 offset:52224
	ds_read_b128 v[182:185], v172 offset:54272
	ds_read_b128 v[190:193], v172 offset:56320
	s_waitcnt vmcnt(6)
	s_waitcnt lgkmcnt(0)
	s_barrier
	v_mfma_f32_16x16x32_bf16 v[60:63], v[128:131], v[144:147], v[60:63]
	v_mfma_f32_16x16x32_bf16 v[56:59], v[136:139], v[144:147], v[56:59]
	v_mfma_f32_16x16x32_bf16 v[44:47], v[128:131], v[166:169], v[44:47]
	v_mfma_f32_16x16x32_bf16 v[40:43], v[136:139], v[166:169], v[40:43]
	v_mfma_f32_16x16x32_bf16 v[28:31], v[128:131], v[178:181], v[28:31]
	v_mfma_f32_16x16x32_bf16 v[24:27], v[136:139], v[178:181], v[24:27]
	v_mfma_f32_16x16x32_bf16 v[12:15], v[128:131], v[186:189], v[12:15]
	v_mfma_f32_16x16x32_bf16 v[8:11], v[136:139], v[186:189], v[8:11]
	v_mfma_f32_16x16x32_bf16 v[60:63], v[132:135], v[148:151], v[60:63]
	v_mfma_f32_16x16x32_bf16 v[56:59], v[140:143], v[148:151], v[56:59]
	v_mfma_f32_16x16x32_bf16 v[44:47], v[132:135], v[174:177], v[44:47]
	v_mfma_f32_16x16x32_bf16 v[40:43], v[140:143], v[174:177], v[40:43]
	v_mfma_f32_16x16x32_bf16 v[28:31], v[132:135], v[182:185], v[28:31]
	v_mfma_f32_16x16x32_bf16 v[24:27], v[140:143], v[182:185], v[24:27]
	v_mfma_f32_16x16x32_bf16 v[12:15], v[132:135], v[190:193], v[12:15]
	v_mfma_f32_16x16x32_bf16 v[8:11], v[140:143], v[190:193], v[8:11]
	v_mfma_f32_16x16x32_bf16 v[52:55], v[194:197], v[144:147], v[52:55]
	v_mfma_f32_16x16x32_bf16 v[48:51], v[202:205], v[144:147], v[48:51]
	s_add_i32 s38, s38, 2
	s_add_u32 s12, s12, 0x8000
	s_addc_u32 s13, s13, 0
	s_add_u32 s36, s36, 0x8000
	s_addc_u32 s37, s37, 0
	v_mfma_f32_16x16x32_bf16 v[36:39], v[194:197], v[166:169], v[36:39]
	v_mfma_f32_16x16x32_bf16 v[32:35], v[202:205], v[166:169], v[32:35]
	v_mfma_f32_16x16x32_bf16 v[20:23], v[194:197], v[178:181], v[20:23]
	v_mfma_f32_16x16x32_bf16 v[16:19], v[202:205], v[178:181], v[16:19]
	v_mfma_f32_16x16x32_bf16 v[4:7], v[194:197], v[186:189], v[4:7]
	v_mfma_f32_16x16x32_bf16 v[0:3], v[202:205], v[186:189], v[0:3]
	v_mfma_f32_16x16x32_bf16 v[52:55], v[198:201], v[148:151], v[52:55]
	v_mfma_f32_16x16x32_bf16 v[48:51], v[206:209], v[148:151], v[48:51]
	v_mfma_f32_16x16x32_bf16 v[36:39], v[198:201], v[174:177], v[36:39]
	v_mfma_f32_16x16x32_bf16 v[32:35], v[206:209], v[174:177], v[32:35]
	v_mfma_f32_16x16x32_bf16 v[20:23], v[198:201], v[182:185], v[20:23]
	v_mfma_f32_16x16x32_bf16 v[16:19], v[206:209], v[182:185], v[16:19]
	v_mfma_f32_16x16x32_bf16 v[4:7], v[198:201], v[190:193], v[4:7]
	s_cmp_gt_u32 s38, 29
	v_mfma_f32_16x16x32_bf16 v[0:3], v[206:209], v[190:193], v[0:3]
	s_barrier
	s_cbranch_scc0 .LBB0_247
	s_branch .Lpeel_done_247
.LBB0_247:
	s_add_u32 s14, s12, 0xfff84000
	s_addc_u32 s15, s13, -1
	s_cmp_eq_u32 s38, 28
	s_cselect_b32 s18, s11, s14
	s_cselect_b32 s19, s5, s15
	s_cselect_b32 s14, s35, s36
	s_cselect_b32 s15, s3, s37
	s_add_u32 s16, s18, 0x4000
	s_addc_u32 s17, s19, 0
	s_add_i32 m0, s25, 0xc000
	v_lshl_add_u64 v[194:195], s[12:13], 0, v[156:157]
	global_load_lds_dwordx4 v[194:195], off
	s_add_i32 m0, s25, 0xe000
	v_lshl_add_u64 v[194:195], s[12:13], 0, v[158:159]
	global_load_lds_dwordx4 v[194:195], off
	s_mov_b32 s39, 0x10000
	v_add_u32_e32 v140, s39, v170
	ds_read_b128 v[128:131], v140
	ds_read_b128 v[136:139], v140 offset:2048
	ds_read_b128 v[132:135], v140 offset:1024
	ds_read_b128 v[140:143], v140 offset:3072
	ds_read_b128 v[144:147], v172
	ds_read_b128 v[166:169], v172 offset:2048
	ds_read_b128 v[178:181], v172 offset:4096
	ds_read_b128 v[186:189], v172 offset:6144
	ds_read_b128 v[148:151], v172 offset:1024
	ds_read_b128 v[174:177], v172 offset:3072
	ds_read_b128 v[182:185], v172 offset:5120
	ds_read_b128 v[190:193], v172 offset:7168
	s_mov_b32 s42, 0x14000
	s_add_i32 s39, s39, s23
	v_add_u32_e32 v152, s42, v170
	ds_read_b128 v[194:197], v152
	ds_read_b128 v[202:205], v152 offset:2048
	ds_read_b128 v[198:201], v152 offset:1024
	ds_read_b128 v[206:209], v152 offset:3072
	s_waitcnt lgkmcnt(0)
	s_barrier
; #define PG8_STAGE(bufoff, gbase, voff) do { _Pragma("unroll") for (int _i = 0; _i < 2; ++_i) \
;         __builtin_amdgcn_global_load_lds((const unsigned*)((const char*)(gbase) + (voff)[_i]), (LAS unsigned*)(lds + (bufoff) + ldsw + _i * 8192), 16, 0, 0); } while (0)
; #define PG8_LDA(dst, b, h) do { _Pragma("unroll") for (int m = 0; m < 4; ++m) _Pragma("unroll") for (int k = 0; k < 2; ++k) dst[m][k] = *(const LAS bf16x8*)(lds + PG8_SA(b, h) + aoff + m * 2048 + k * 1024); } while (0)
; #define PG8_LDB(dst, b, h) do { _Pragma("unroll") for (int n = 0; n < 2; ++n) _Pragma("unroll") for (int k = 0; k < 2; ++k) dst[n][k] = *(const LAS bf16x8*)(lds + PG8_SB(b, h) + boff + n * 2048 + k * 1024); } while (0)
; #define PG8_MMA(ai, bj, At, Bt) do { __builtin_amdgcn_s_setprio(1); _Pragma("unroll") for (int m = 0; m < 4; ++m) _Pragma("unroll") for (int n = 0; n < 2; ++n) _Pragma("unroll") for (int k = 0; k < 2; ++k) \
;         acc[ai][bj][m][n] = __builtin_amdgcn_mfma_f32_16x16x32_bf16(Bt[n][k], At[m][k], acc[ai][bj][m][n], 0, 0, 0); __builtin_amdgcn_s_setprio(0); } while (0)
; #define PG8_WAIT_V(n) asm volatile("s_waitcnt vmcnt(" #n ")" ::: "memory")
; #define PG8_WAIT_L(n) asm volatile("s_waitcnt lgkmcnt(" #n ")" ::: "memory")
; template <class Epi>
; __device__ __forceinline__ void gemm_phase(LAS unsigned char* lds, const Gemm g, const StaticOrder& S, const Epi& E) {
;     ...
;         for (int t = 0; t < nt; t += 2) {
;             const bool last = (t == nt - 2);
;             const char* a1 = cA + (size_t)(t + 1) * kstep;
;             const char* a2 = last ? nA : cA + (size_t)(t + 2) * kstep; const char* b2 = last ? nB : cB + (size_t)(t + 2) * kstep;
;             const char* a3 = a2 + kstep; const char* b3 = b2 + kstep;
;             PG8_LDB(B0, 0, 0); PG8_SCHED; PG8_LDA(At, 0, 0); PG8_STAGE(PG8_SA(1, 1), a1 + hstepA, voffA);
;             PG8_WAIT_L(8); PG8_BAR; PG8_WAIT_L(0); PG8_MMA(0, 0, At, B0); PG8_BAR; PG8_SCHED;
;             PG8_LDB(B1, 0, 1); PG8_STAGE(PG8_SB(0, 0), b2, voffB);
;             PG8_BAR; PG8_WAIT_L(0); PG8_MMA(0, 1, At, B1); PG8_BAR;
;             PG8_LDA(At, 0, 1); PG8_STAGE(PG8_SA(0, 0), a2, voffA);
;             PG8_BAR; PG8_WAIT_L(0); PG8_MMA(1, 0, At, B0); PG8_BAR; PG8_SCHED;
;             PG8_STAGE(PG8_SB(0, 1), b2 + hstepB, voffB);
;             PG8_WAIT_V(6); PG8_BAR; PG8_MMA(1, 1, At, B1); PG8_BAR;
	v_mfma_f32_16x16x32_bf16 v[124:127], v[128:131], v[144:147], v[124:127]
	v_mfma_f32_16x16x32_bf16 v[120:123], v[136:139], v[144:147], v[120:123]
	v_mfma_f32_16x16x32_bf16 v[108:111], v[128:131], v[166:169], v[108:111]
	v_mfma_f32_16x16x32_bf16 v[104:107], v[136:139], v[166:169], v[104:107]
	v_mfma_f32_16x16x32_bf16 v[92:95], v[128:131], v[178:181], v[92:95]
	v_mfma_f32_16x16x32_bf16 v[88:91], v[136:139], v[178:181], v[88:91]
	v_mfma_f32_16x16x32_bf16 v[76:79], v[128:131], v[186:189], v[76:79]
	v_mfma_f32_16x16x32_bf16 v[72:75], v[136:139], v[186:189], v[72:75]
	v_mfma_f32_16x16x32_bf16 v[124:127], v[132:135], v[148:151], v[124:127]
	v_mfma_f32_16x16x32_bf16 v[120:123], v[140:143], v[148:151], v[120:123]
	v_mfma_f32_16x16x32_bf16 v[108:111], v[132:135], v[174:177], v[108:111]
	v_mfma_f32_16x16x32_bf16 v[104:107], v[140:143], v[174:177], v[104:107]
	v_mfma_f32_16x16x32_bf16 v[92:95], v[132:135], v[182:185], v[92:95]
	v_mfma_f32_16x16x32_bf16 v[88:91], v[140:143], v[182:185], v[88:91]
	v_mfma_f32_16x16x32_bf16 v[76:79], v[132:135], v[190:193], v[76:79]
	v_mfma_f32_16x16x32_bf16 v[72:75], v[140:143], v[190:193], v[72:75]
	v_mfma_f32_16x16x32_bf16 v[116:119], v[194:197], v[144:147], v[116:119]
	v_mfma_f32_16x16x32_bf16 v[112:115], v[202:205], v[144:147], v[112:115]
	v_mfma_f32_16x16x32_bf16 v[100:103], v[194:197], v[166:169], v[100:103]
	v_mfma_f32_16x16x32_bf16 v[96:99], v[202:205], v[166:169], v[96:99]
	v_mfma_f32_16x16x32_bf16 v[84:87], v[194:197], v[178:181], v[84:87]
	v_mfma_f32_16x16x32_bf16 v[80:83], v[202:205], v[178:181], v[80:83]
	v_mfma_f32_16x16x32_bf16 v[68:71], v[194:197], v[186:189], v[68:71]
	v_mfma_f32_16x16x32_bf16 v[64:67], v[202:205], v[186:189], v[64:67]
	v_mfma_f32_16x16x32_bf16 v[116:119], v[198:201], v[148:151], v[116:119]
	v_mfma_f32_16x16x32_bf16 v[112:115], v[206:209], v[148:151], v[112:115]
	v_mfma_f32_16x16x32_bf16 v[100:103], v[198:201], v[174:177], v[100:103]
	v_mfma_f32_16x16x32_bf16 v[96:99], v[206:209], v[174:177], v[96:99]
	v_mfma_f32_16x16x32_bf16 v[84:87], v[198:201], v[182:185], v[84:87]
	v_mfma_f32_16x16x32_bf16 v[80:83], v[206:209], v[182:185], v[80:83]
	v_mfma_f32_16x16x32_bf16 v[68:71], v[198:201], v[190:193], v[68:71]
	v_mfma_f32_16x16x32_bf16 v[64:67], v[206:209], v[190:193], v[64:67]
	s_barrier
	s_mov_b32 m0, s39
	v_lshl_add_u64 v[210:211], s[14:15], 0, v[156:157]
	global_load_lds_dwordx4 v[210:211], off
	s_add_i32 m0, s39, 0x2000
	v_lshl_add_u64 v[210:211], s[14:15], 0, v[158:159]
	global_load_lds_dwordx4 v[210:211], off
	s_mov_b32 m0, s25
	v_lshl_add_u64 v[210:211], s[18:19], 0, v[156:157]
	global_load_lds_dwordx4 v[210:211], off
	s_mov_b32 m0, s26
	v_lshl_add_u64 v[210:211], s[18:19], 0, v[158:159]
	global_load_lds_dwordx4 v[210:211], off
	s_add_u32 s40, s14, 0x80000
	s_addc_u32 s41, s15, 0
	s_add_i32 s39, s42, s23
	s_mov_b32 m0, s39
	v_lshl_add_u64 v[210:211], s[40:41], 0, v[156:157]
	global_load_lds_dwordx4 v[210:211], off
	s_add_i32 m0, s39, 0x2000
	v_lshl_add_u64 v[210:211], s[40:41], 0, v[158:159]
	global_load_lds_dwordx4 v[210:211], off
	ds_read_b128 v[144:147], v172 offset:16384
	ds_read_b128 v[166:169], v172 offset:18432
	ds_read_b128 v[178:181], v172 offset:20480
	ds_read_b128 v[186:189], v172 offset:22528
	ds_read_b128 v[148:151], v172 offset:17408
	ds_read_b128 v[174:177], v172 offset:19456
	ds_read_b128 v[182:185], v172 offset:21504
	ds_read_b128 v[190:193], v172 offset:23552
	s_waitcnt vmcnt(6)
	s_waitcnt lgkmcnt(0)
	s_barrier
	v_mfma_f32_16x16x32_bf16 v[60:63], v[128:131], v[144:147], v[60:63]
	v_mfma_f32_16x16x32_bf16 v[56:59], v[136:139], v[144:147], v[56:59]
	v_mfma_f32_16x16x32_bf16 v[44:47], v[128:131], v[166:169], v[44:47]
	v_mfma_f32_16x16x32_bf16 v[40:43], v[136:139], v[166:169], v[40:43]
	v_mfma_f32_16x16x32_bf16 v[28:31], v[128:131], v[178:181], v[28:31]
	v_mfma_f32_16x16x32_bf16 v[24:27], v[136:139], v[178:181], v[24:27]
	v_mfma_f32_16x16x32_bf16 v[12:15], v[128:131], v[186:189], v[12:15]
	v_mfma_f32_16x16x32_bf16 v[8:11], v[136:139], v[186:189], v[8:11]
	v_mfma_f32_16x16x32_bf16 v[60:63], v[132:135], v[148:151], v[60:63]
	v_mfma_f32_16x16x32_bf16 v[56:59], v[140:143], v[148:151], v[56:59]
	v_mfma_f32_16x16x32_bf16 v[44:47], v[132:135], v[174:177], v[44:47]
	v_mfma_f32_16x16x32_bf16 v[40:43], v[140:143], v[174:177], v[40:43]
	v_mfma_f32_16x16x32_bf16 v[28:31], v[132:135], v[182:185], v[28:31]
	v_mfma_f32_16x16x32_bf16 v[24:27], v[140:143], v[182:185], v[24:27]
	v_mfma_f32_16x16x32_bf16 v[12:15], v[132:135], v[190:193], v[12:15]
	v_mfma_f32_16x16x32_bf16 v[8:11], v[140:143], v[190:193], v[8:11]
	v_mfma_f32_16x16x32_bf16 v[52:55], v[194:197], v[144:147], v[52:55]
	v_mfma_f32_16x16x32_bf16 v[48:51], v[202:205], v[144:147], v[48:51]
	s_add_i32 s39, 0, 0x18000
	v_add_u32_e32 v140, s39, v170
	v_mfma_f32_16x16x32_bf16 v[36:39], v[194:197], v[166:169], v[36:39]
	v_mfma_f32_16x16x32_bf16 v[32:35], v[202:205], v[166:169], v[32:35]
	v_mfma_f32_16x16x32_bf16 v[20:23], v[194:197], v[178:181], v[20:23]
	v_mfma_f32_16x16x32_bf16 v[16:19], v[202:205], v[178:181], v[16:19]
	v_mfma_f32_16x16x32_bf16 v[4:7], v[194:197], v[186:189], v[4:7]
	v_mfma_f32_16x16x32_bf16 v[0:3], v[202:205], v[186:189], v[0:3]
	v_mfma_f32_16x16x32_bf16 v[52:55], v[198:201], v[148:151], v[52:55]
	v_mfma_f32_16x16x32_bf16 v[48:51], v[206:209], v[148:151], v[48:51]
	v_mfma_f32_16x16x32_bf16 v[36:39], v[198:201], v[174:177], v[36:39]
	v_mfma_f32_16x16x32_bf16 v[32:35], v[206:209], v[174:177], v[32:35]
	v_mfma_f32_16x16x32_bf16 v[20:23], v[198:201], v[182:185], v[20:23]
	v_mfma_f32_16x16x32_bf16 v[16:19], v[206:209], v[182:185], v[16:19]
	v_mfma_f32_16x16x32_bf16 v[4:7], v[198:201], v[190:193], v[4:7]
	v_mfma_f32_16x16x32_bf16 v[0:3], v[206:209], v[190:193], v[0:3]
	s_barrier
; #define PG8_STAGE(bufoff, gbase, voff) do { _Pragma("unroll") for (int _i = 0; _i < 2; ++_i) \
;         __builtin_amdgcn_global_load_lds((const unsigned*)((const char*)(gbase) + (voff)[_i]), (LAS unsigned*)(lds + (bufoff) + ldsw + _i * 8192), 16, 0, 0); } while (0)
; #define PG8_LDA(dst, b, h) do { _Pragma("unroll") for (int m = 0; m < 4; ++m) _Pragma("unroll") for (int k = 0; k < 2; ++k) dst[m][k] = *(const LAS bf16x8*)(lds + PG8_SA(b, h) + aoff + m * 2048 + k * 1024); } while (0)
; #define PG8_LDB(dst, b, h) do { _Pragma("unroll") for (int n = 0; n < 2; ++n) _Pragma("unroll") for (int k = 0; k < 2; ++k) dst[n][k] = *(const LAS bf16x8*)(lds + PG8_SB(b, h) + boff + n * 2048 + k * 1024); } while (0)
; #define PG8_MMA(ai, bj, At, Bt) do { __builtin_amdgcn_s_setprio(1); _Pragma("unroll") for (int m = 0; m < 4; ++m) _Pragma("unroll") for (int n = 0; n < 2; ++n) _Pragma("unroll") for (int k = 0; k < 2; ++k) \
;         acc[ai][bj][m][n] = __builtin_amdgcn_mfma_f32_16x16x32_bf16(Bt[n][k], At[m][k], acc[ai][bj][m][n], 0, 0, 0); __builtin_amdgcn_s_setprio(0); } while (0)
; #define PG8_WAIT_V(n) asm volatile("s_waitcnt vmcnt(" #n ")" ::: "memory")
; #define PG8_WAIT_L(n) asm volatile("s_waitcnt lgkmcnt(" #n ")" ::: "memory")
; #define PG8_BAR __builtin_amdgcn_s_barrier()
; #define PG8_SCHED __builtin_amdgcn_sched_barrier(0)
; template <class Epi>
; __device__ __forceinline__ void gemm_phase(LAS unsigned char* lds, const Gemm g, const StaticOrder& S, const Epi& E) {
;     ...
;             PG8_LDB(B0, 1, 0); PG8_SCHED; PG8_LDA(At, 1, 0); PG8_STAGE(PG8_SA(0, 1), a2 + hstepA, voffA);
;             PG8_WAIT_L(8); PG8_BAR; PG8_WAIT_L(0); PG8_MMA(0, 0, At, B0); PG8_BAR; PG8_SCHED;
;             PG8_LDB(B1, 1, 1); PG8_STAGE(PG8_SB(1, 0), b3, voffB);
;             PG8_BAR; PG8_WAIT_L(0); PG8_MMA(0, 1, At, B1); PG8_BAR;
;             PG8_LDA(At, 1, 1); PG8_STAGE(PG8_SA(1, 0), a3, voffA);
;             PG8_BAR; PG8_WAIT_L(0); PG8_MMA(1, 0, At, B0); PG8_BAR; PG8_SCHED;
;             PG8_STAGE(PG8_SB(1, 1), b3 + hstepB, voffB);
;             PG8_WAIT_V(6); PG8_BAR; PG8_MMA(1, 1, At, B1); PG8_BAR;
;         }
	s_add_u32 s18, s18, 0x80000
	s_addc_u32 s19, s19, 0
	s_mov_b32 m0, s27
	v_lshl_add_u64 v[194:195], s[18:19], 0, v[156:157]
	global_load_lds_dwordx4 v[194:195], off
	s_mov_b32 m0, s28
	v_lshl_add_u64 v[194:195], s[18:19], 0, v[158:159]
	global_load_lds_dwordx4 v[194:195], off
	ds_read_b128 v[128:131], v140
	ds_read_b128 v[136:139], v140 offset:2048
	ds_read_b128 v[132:135], v140 offset:1024
	ds_read_b128 v[140:143], v140 offset:3072
	ds_read_b128 v[144:147], v172 offset:32768
	ds_read_b128 v[166:169], v172 offset:34816
	ds_read_b128 v[178:181], v172 offset:36864
	ds_read_b128 v[186:189], v172 offset:38912
	ds_read_b128 v[148:151], v172 offset:33792
	ds_read_b128 v[174:177], v172 offset:35840
	ds_read_b128 v[182:185], v172 offset:37888
	ds_read_b128 v[190:193], v172 offset:39936
	s_mov_b32 s40, 0x1c000
	s_add_u32 s18, s14, 0x4000
	s_addc_u32 s19, s15, 0
	s_add_i32 s39, s39, s23
	v_add_u32_e32 v152, s40, v170
	ds_read_b128 v[194:197], v152
	ds_read_b128 v[202:205], v152 offset:2048
	ds_read_b128 v[198:201], v152 offset:1024
	ds_read_b128 v[206:209], v152 offset:3072
	s_waitcnt lgkmcnt(0)
	s_barrier
	v_mfma_f32_16x16x32_bf16 v[124:127], v[128:131], v[144:147], v[124:127]
	v_mfma_f32_16x16x32_bf16 v[120:123], v[136:139], v[144:147], v[120:123]
	v_mfma_f32_16x16x32_bf16 v[108:111], v[128:131], v[166:169], v[108:111]
	v_mfma_f32_16x16x32_bf16 v[104:107], v[136:139], v[166:169], v[104:107]
	v_mfma_f32_16x16x32_bf16 v[92:95], v[128:131], v[178:181], v[92:95]
	v_mfma_f32_16x16x32_bf16 v[88:91], v[136:139], v[178:181], v[88:91]
	v_mfma_f32_16x16x32_bf16 v[76:79], v[128:131], v[186:189], v[76:79]
	v_mfma_f32_16x16x32_bf16 v[72:75], v[136:139], v[186:189], v[72:75]
	v_mfma_f32_16x16x32_bf16 v[124:127], v[132:135], v[148:151], v[124:127]
	v_mfma_f32_16x16x32_bf16 v[120:123], v[140:143], v[148:151], v[120:123]
	v_mfma_f32_16x16x32_bf16 v[108:111], v[132:135], v[174:177], v[108:111]
	v_mfma_f32_16x16x32_bf16 v[104:107], v[140:143], v[174:177], v[104:107]
	v_mfma_f32_16x16x32_bf16 v[92:95], v[132:135], v[182:185], v[92:95]
	v_mfma_f32_16x16x32_bf16 v[88:91], v[140:143], v[182:185], v[88:91]
	v_mfma_f32_16x16x32_bf16 v[76:79], v[132:135], v[190:193], v[76:79]
	v_mfma_f32_16x16x32_bf16 v[72:75], v[140:143], v[190:193], v[72:75]
	v_mfma_f32_16x16x32_bf16 v[116:119], v[194:197], v[144:147], v[116:119]
	v_mfma_f32_16x16x32_bf16 v[112:115], v[202:205], v[144:147], v[112:115]
	v_mfma_f32_16x16x32_bf16 v[100:103], v[194:197], v[166:169], v[100:103]
	v_mfma_f32_16x16x32_bf16 v[96:99], v[202:205], v[166:169], v[96:99]
	v_mfma_f32_16x16x32_bf16 v[84:87], v[194:197], v[178:181], v[84:87]
	v_mfma_f32_16x16x32_bf16 v[80:83], v[202:205], v[178:181], v[80:83]
	v_mfma_f32_16x16x32_bf16 v[68:71], v[194:197], v[186:189], v[68:71]
	v_mfma_f32_16x16x32_bf16 v[64:67], v[202:205], v[186:189], v[64:67]
	v_mfma_f32_16x16x32_bf16 v[116:119], v[198:201], v[148:151], v[116:119]
	v_mfma_f32_16x16x32_bf16 v[112:115], v[206:209], v[148:151], v[112:115]
	v_mfma_f32_16x16x32_bf16 v[100:103], v[198:201], v[174:177], v[100:103]
	v_mfma_f32_16x16x32_bf16 v[96:99], v[206:209], v[174:177], v[96:99]
	v_mfma_f32_16x16x32_bf16 v[84:87], v[198:201], v[182:185], v[84:87]
	v_mfma_f32_16x16x32_bf16 v[80:83], v[206:209], v[182:185], v[80:83]
	v_mfma_f32_16x16x32_bf16 v[68:71], v[198:201], v[190:193], v[68:71]
	v_mfma_f32_16x16x32_bf16 v[64:67], v[206:209], v[190:193], v[64:67]
	s_barrier
	s_mov_b32 m0, s39
	v_lshl_add_u64 v[210:211], s[18:19], 0, v[156:157]
	global_load_lds_dwordx4 v[210:211], off
	s_add_i32 m0, s39, 0x2000
	v_lshl_add_u64 v[210:211], s[18:19], 0, v[158:159]
	global_load_lds_dwordx4 v[210:211], off
	s_mov_b32 m0, s29
	v_lshl_add_u64 v[210:211], s[16:17], 0, v[156:157]
	global_load_lds_dwordx4 v[210:211], off
	s_mov_b32 m0, s30
	v_lshl_add_u64 v[210:211], s[16:17], 0, v[158:159]
	global_load_lds_dwordx4 v[210:211], off
	s_add_u32 s14, s14, 0x84000
	s_addc_u32 s15, s15, 0
	s_add_i32 s16, s40, s23
	s_mov_b32 m0, s16
	v_lshl_add_u64 v[210:211], s[14:15], 0, v[156:157]
	global_load_lds_dwordx4 v[210:211], off
	s_add_i32 m0, s16, 0x2000
	v_lshl_add_u64 v[210:211], s[14:15], 0, v[158:159]
	global_load_lds_dwordx4 v[210:211], off
	ds_read_b128 v[144:147], v172 offset:49152
	ds_read_b128 v[166:169], v172 offset:51200
	ds_read_b128 v[178:181], v172 offset:53248
	ds_read_b128 v[186:189], v172 offset:55296
	ds_read_b128 v[148:151], v172 offset:50176
	ds_read_b128 v[174:177], v172 offset:52224
	ds_read_b128 v[182:185], v172 offset:54272
	ds_read_b128 v[190:193], v172 offset:56320
	s_waitcnt vmcnt(6)
	s_waitcnt lgkmcnt(0)
	s_barrier
	v_mfma_f32_16x16x32_bf16 v[60:63], v[128:131], v[144:147], v[60:63]
	v_mfma_f32_16x16x32_bf16 v[56:59], v[136:139], v[144:147], v[56:59]
	v_mfma_f32_16x16x32_bf16 v[44:47], v[128:131], v[166:169], v[44:47]
	v_mfma_f32_16x16x32_bf16 v[40:43], v[136:139], v[166:169], v[40:43]
	v_mfma_f32_16x16x32_bf16 v[28:31], v[128:131], v[178:181], v[28:31]
	v_mfma_f32_16x16x32_bf16 v[24:27], v[136:139], v[178:181], v[24:27]
	v_mfma_f32_16x16x32_bf16 v[12:15], v[128:131], v[186:189], v[12:15]
	v_mfma_f32_16x16x32_bf16 v[8:11], v[136:139], v[186:189], v[8:11]
	v_mfma_f32_16x16x32_bf16 v[60:63], v[132:135], v[148:151], v[60:63]
	v_mfma_f32_16x16x32_bf16 v[56:59], v[140:143], v[148:151], v[56:59]
	v_mfma_f32_16x16x32_bf16 v[44:47], v[132:135], v[174:177], v[44:47]
	v_mfma_f32_16x16x32_bf16 v[40:43], v[140:143], v[174:177], v[40:43]
	v_mfma_f32_16x16x32_bf16 v[28:31], v[132:135], v[182:185], v[28:31]
	v_mfma_f32_16x16x32_bf16 v[24:27], v[140:143], v[182:185], v[24:27]
	v_mfma_f32_16x16x32_bf16 v[12:15], v[132:135], v[190:193], v[12:15]
	v_mfma_f32_16x16x32_bf16 v[8:11], v[140:143], v[190:193], v[8:11]
	v_mfma_f32_16x16x32_bf16 v[52:55], v[194:197], v[144:147], v[52:55]
	v_mfma_f32_16x16x32_bf16 v[48:51], v[202:205], v[144:147], v[48:51]
	s_add_i32 s38, s38, 2
	s_add_u32 s12, s12, 0x8000
	s_addc_u32 s13, s13, 0
	s_add_u32 s36, s36, 0x8000
	s_addc_u32 s37, s37, 0
	v_mfma_f32_16x16x32_bf16 v[36:39], v[194:197], v[166:169], v[36:39]
	v_mfma_f32_16x16x32_bf16 v[32:35], v[202:205], v[166:169], v[32:35]
	v_mfma_f32_16x16x32_bf16 v[20:23], v[194:197], v[178:181], v[20:23]
	v_mfma_f32_16x16x32_bf16 v[16:19], v[202:205], v[178:181], v[16:19]
	v_mfma_f32_16x16x32_bf16 v[4:7], v[194:197], v[186:189], v[4:7]
	v_mfma_f32_16x16x32_bf16 v[0:3], v[202:205], v[186:189], v[0:3]
	v_mfma_f32_16x16x32_bf16 v[52:55], v[198:201], v[148:151], v[52:55]
	v_mfma_f32_16x16x32_bf16 v[48:51], v[206:209], v[148:151], v[48:51]
	v_mfma_f32_16x16x32_bf16 v[36:39], v[198:201], v[174:177], v[36:39]
	v_mfma_f32_16x16x32_bf16 v[32:35], v[206:209], v[174:177], v[32:35]
	v_mfma_f32_16x16x32_bf16 v[20:23], v[198:201], v[182:185], v[20:23]
	v_mfma_f32_16x16x32_bf16 v[16:19], v[206:209], v[182:185], v[16:19]
	v_mfma_f32_16x16x32_bf16 v[4:7], v[198:201], v[190:193], v[4:7]
	s_cmp_gt_u32 s38, 29
	v_mfma_f32_16x16x32_bf16 v[0:3], v[206:209], v[190:193], v[0:3]
	s_barrier
	s_cbranch_scc0 .LBB0_247
